# ph_mix row loop: all 56 row loads issued up front into unused VGPRs, counted waits + copies replace the serialised load-wait ladder
# speedup vs baseline: 1.0321x; 1.0321x over previous
.LBB0_1302:
	s_or_b64 exec, exec, s[40:41]
	s_lshl_b32 s2, s92, 3
	s_add_i32 s38, s2, s93
	s_cmp_ge_i32 s38, s90
	s_waitcnt lgkmcnt(0)
	s_barrier
	s_cbranch_scc1 .LBB0_1306
	v_lshlrev_b32_e32 v0, 2, v10
	v_lshlrev_b32_e32 v2, 3, v10
	s_lshl_b32 s2, s93, 12
	v_ashrrev_i32_e32 v3, 31, v2
	v_add_u32_e32 v4, 0x100, v0
	v_add_u32_e32 v6, 0x200, v0
	v_add_u32_e32 v8, 0x300, v0
	s_add_i32 s2, s2, 0
	s_ashr_i32 s39, s38, 31
	s_lshl_b32 s40, s77, 3
	s_waitcnt vmcnt(27)
	v_lshl_add_u32 v58, v10, 5, 0
	v_ashrrev_i32_e32 v1, 31, v0
	v_lshlrev_b32_e32 v10, 4, v10
	v_ashrrev_i32_e32 v5, 31, v4
	v_ashrrev_i32_e32 v7, 31, v6
	v_ashrrev_i32_e32 v9, 31, v8
	s_add_i32 s2, s2, 0x10000
	s_lshl_b64 s[4:5], s[38:39], 12
	v_lshlrev_b64 v[2:3], 1, v[2:3]
	s_lshl_b64 s[8:9], s[38:39], 10
	v_add_u32_e32 v59, 0, v10
	s_waitcnt vmcnt(26)
	v_add_u32_e32 v60, s2, v10
	v_lshlrev_b64 v[10:11], 1, v[0:1]
	s_ashr_i32 s41, s40, 31
	v_lshl_add_u64 v[14:15], s[4:5], 0, v[2:3]
	v_lshl_add_u64 v[16:17], s[8:9], 0, v[2:3]
	s_lshl_b64 s[8:9], s[38:39], 11
	v_lshl_add_u64 v[20:21], v[0:1], 2, s[4:5]
	v_lshlrev_b64 v[0:1], 1, v[8:9]
	v_lshlrev_b64 v[2:3], 1, v[6:7]
	v_lshlrev_b64 v[4:5], 1, v[4:5]
	v_mov_b32_e32 v6, 0x2e00
	v_lshl_add_u64 v[12:13], s[4:5], 0, v[10:11]
	s_lshl_b64 s[42:43], s[40:41], 12
	s_lshl_b64 s[44:45], s[40:41], 10
	v_lshl_add_u64 v[18:19], s[8:9], 0, v[10:11]
	s_lshl_b64 s[46:47], s[40:41], 11
	v_lshl_add_u64 v[22:23], s[8:9], 0, v[0:1]
	v_lshl_add_u64 v[24:25], s[8:9], 0, v[2:3]
	v_lshl_add_u64 v[26:27], s[8:9], 0, v[4:5]
	v_mad_i64_i32 v[28:29], s[4:5], s38, v6, v[0:1]
	s_mul_i32 s48, s77, 0x17000
	s_mul_hi_i32 s49, s40, 0x2e00
	v_mad_i64_i32 v[30:31], s[4:5], s38, v6, v[2:3]
	v_mad_i64_i32 v[32:33], s[4:5], s38, v6, v[4:5]
	v_mad_i64_i32 v[34:35], s[4:5], s38, v6, v[10:11]
	s_movk_i32 s10, 0x1fff
	s_mov_b32 s11, 0x21401000
	s_mov_b32 s12, 0x2ed00000
	s_mov_b32 s13, 0x21402000
	s_mov_b32 s24, 0x49900000
	s_waitcnt vmcnt(4)
	v_mov_b32_e32 v84, 0x3a27c5ac
	v_mbcnt_lo_u32_b32 v85, -1, 0
	v_mbcnt_hi_u32_b32 v85, -1, v85
	v_lshlrev_b32_e32 v86, 3, v85
	v_lshlrev_b32_e32 v85, 4, v85
	v_add_u32_e32 v87, 0x35100000, v86
	v_add_u32_e32 v88, 0x39300000, v86
	v_add_u32_e32 v86, 0x21401200, v86
	v_add_u32_e32 v85, 0x3b400000, v85
.LBB0_1304:
	s_cmpk_lt_i32 s38, 0x4000
	s_cselect_b32 s2, s10, 0xff
	s_and_b32 s6, s2, s38
	s_cmp_eq_u32 s6, 0
	s_cselect_b32 s4, 0, 0xffffd200
	s_cmp_eq_u32 s6, s2
	s_cselect_b32 s5, 0, 0x2e00
	s_mul_i32 s2, s38, 0x2e00
	v_add_u32_e32 v91, s2, v86
	s_lshl_b32 s2, s38, 12
	v_add_u32_e32 v89, s2, v85
	s_lshl_b32 s2, s38, 11
	v_add_u32_e32 v97, s2, v87
	v_add_u32_e32 v99, s2, v88
	v_add_u32_e32 v90, 0x4200000, v89
	v_add_u32_e32 v98, 0x2100000, v97
	v_add_u32_e32 v92, 0x1000, v91
	v_add_u32_e32 v93, s4, v91
	v_add_u32_e32 v95, s5, v91
	v_add_u32_e32 v94, 0x1000, v93
	v_add_u32_e32 v96, 0x1000, v95
	global_load_dwordx4 v[100:103], v89, s[74:75]
	global_load_dwordx4 v[104:107], v90, s[74:75]
	global_load_dwordx2 v[108:109], v91, s[74:75]
	global_load_dwordx2 v[110:111], v92, s[74:75]
	global_load_dwordx2 v[112:113], v91, s[74:75] offset:2048
	global_load_dwordx2 v[114:115], v93, s[74:75]
	global_load_dwordx2 v[116:117], v94, s[74:75]
	global_load_dwordx2 v[118:119], v93, s[74:75] offset:2048
	global_load_dwordx2 v[120:121], v97, s[74:75]
	global_load_dwordx2 v[122:123], v95, s[74:75]
	global_load_dwordx2 v[124:125], v96, s[74:75]
	global_load_dwordx2 v[126:127], v95, s[74:75] offset:2048
	global_load_dwordx2 v[128:129], v98, s[74:75]
	global_load_dwordx2 v[130:131], v99, s[74:75]
	global_load_dwordx4 v[132:135], v89, s[74:75] offset:1024
	global_load_dwordx4 v[136:139], v90, s[74:75] offset:1024
	global_load_dwordx2 v[140:141], v91, s[74:75] offset:512
	global_load_dwordx2 v[142:143], v92, s[74:75] offset:512
	global_load_dwordx2 v[144:145], v91, s[74:75] offset:2560
	global_load_dwordx2 v[146:147], v93, s[74:75] offset:512
	global_load_dwordx2 v[148:149], v94, s[74:75] offset:512
	global_load_dwordx2 v[150:151], v93, s[74:75] offset:2560
	global_load_dwordx2 v[152:153], v97, s[74:75] offset:512
	global_load_dwordx2 v[154:155], v95, s[74:75] offset:512
	global_load_dwordx2 v[156:157], v96, s[74:75] offset:512
	global_load_dwordx2 v[158:159], v95, s[74:75] offset:2560
	global_load_dwordx2 v[160:161], v98, s[74:75] offset:512
	global_load_dwordx2 v[162:163], v99, s[74:75] offset:512
	global_load_dwordx4 v[164:167], v89, s[74:75] offset:2048
	global_load_dwordx4 v[168:171], v90, s[74:75] offset:2048
	global_load_dwordx2 v[172:173], v91, s[74:75] offset:1024
	global_load_dwordx2 v[174:175], v92, s[74:75] offset:1024
	global_load_dwordx2 v[176:177], v91, s[74:75] offset:3072
	global_load_dwordx2 v[178:179], v93, s[74:75] offset:1024
	global_load_dwordx2 v[180:181], v94, s[74:75] offset:1024
	global_load_dwordx2 v[182:183], v93, s[74:75] offset:3072
	global_load_dwordx2 v[184:185], v97, s[74:75] offset:1024
	global_load_dwordx2 v[186:187], v95, s[74:75] offset:1024
	global_load_dwordx2 v[188:189], v96, s[74:75] offset:1024
	global_load_dwordx2 v[190:191], v95, s[74:75] offset:3072
	global_load_dwordx2 v[192:193], v98, s[74:75] offset:1024
	global_load_dwordx2 v[194:195], v99, s[74:75] offset:1024
	global_load_dwordx4 v[196:199], v89, s[74:75] offset:3072
	global_load_dwordx4 v[200:203], v90, s[74:75] offset:3072
	global_load_dwordx2 v[204:205], v91, s[74:75] offset:1536
	global_load_dwordx2 v[206:207], v92, s[74:75] offset:1536
	global_load_dwordx2 v[210:211], v91, s[74:75] offset:3584
	global_load_dwordx2 v[212:213], v93, s[74:75] offset:1536
	global_load_dwordx2 v[214:215], v94, s[74:75] offset:1536
	global_load_dwordx2 v[216:217], v93, s[74:75] offset:3584
	global_load_dwordx2 v[218:219], v99, s[74:75] offset:1536
	global_load_dwordx2 v[220:221], v97, s[74:75] offset:1536
	global_load_dwordx2 v[222:223], v95, s[74:75] offset:1536
	global_load_dwordx2 v[224:225], v96, s[74:75] offset:1536
	global_load_dwordx2 v[226:227], v95, s[74:75] offset:3584
	global_load_dwordx2 v[228:229], v98, s[74:75] offset:1536
	s_cmpk_lt_i32 s38, 0x4000
	s_cselect_b32 s2, s10, 0xff
	s_and_b32 s6, s2, s38
	s_cmp_eq_u32 s6, 0
	s_cselect_b64 s[52:53], -1, 0
	s_and_b64 s[4:5], s[52:53], exec
	s_cselect_b32 s4, 0, 0xffffd200
	s_cselect_b32 s5, 0, -1
	s_cmp_eq_u32 s6, s2
	v_lshl_add_u64 v[4:5], s[74:75], 0, v[20:21]
	s_mov_b32 s6, 0x3b400000
	v_add_co_u32_e32 v36, vcc, s6, v4
	s_mov_b32 s6, 0x3f600000
	s_nop 0
	v_addc_co_u32_e32 v37, vcc, 0, v5, vcc
	v_add_co_u32_e32 v38, vcc, s6, v4
	s_waitcnt vmcnt(55)
	v_mov_b32_e32 v0, v100
	v_mov_b32_e32 v1, v101
	v_mov_b32_e32 v2, v102
	v_mov_b32_e32 v3, v103
	s_nop 0
	v_addc_co_u32_e32 v39, vcc, 0, v5, vcc
	s_waitcnt vmcnt(54)
	v_mov_b32_e32 v4, v104
	v_mov_b32_e32 v5, v105
	v_mov_b32_e32 v6, v106
	v_mov_b32_e32 v7, v107
	s_cselect_b64 s[50:51], -1, 0
	s_and_b64 s[8:9], s[50:51], exec
	s_cselect_b32 s2, 0, 0x2e00
	s_add_u32 s54, s74, s4
	s_addc_u32 s55, s75, s5
	v_lshl_add_u64 v[44:45], s[54:55], 0, v[34:35]
	s_add_u32 s56, s74, s2
	s_addc_u32 s57, s75, 0
	s_mov_b32 s2, 0x39300000
	s_add_i32 s38, s38, s40
	v_lshl_add_u64 v[20:21], v[20:21], 0, s[42:43]
	s_cmp_lt_i32 s38, s90
	v_pk_add_f32 v[2:3], v[2:3], v[6:7]
	v_pk_add_f32 v[0:1], v[0:1], v[4:5]
	v_mov_b32_e32 v7, v3
	v_pk_mov_b32 v[4:5], v[0:1], v[2:3] op_sel:[1,0]
	v_mov_b32_e32 v6, v0
	v_pk_add_f32 v[4:5], v[4:5], v[6:7]
	s_nop 0
	v_add_f32_e32 v4, v4, v5
	s_nop 1
	v_add_f32_dpp v4, v4, v4 quad_perm:[1,0,3,2] row_mask:0xf bank_mask:0xf bound_ctrl:1
	s_nop 1
	v_add_f32_dpp v4, v4, v4 quad_perm:[2,3,0,1] row_mask:0xf bank_mask:0xf bound_ctrl:1
	s_nop 1
	v_add_f32_dpp v4, v4, v4 row_half_mirror row_mask:0xf bank_mask:0xf bound_ctrl:1
	s_nop 1
	v_add_f32_dpp v4, v4, v4 row_mirror row_mask:0xf bank_mask:0xf bound_ctrl:1
	v_fmamk_f32 v1, v4, 0xbc800000, v1
	v_fmac_f32_e32 v0, 0xbc800000, v4
	v_fmamk_f32 v3, v4, 0xbc800000, v3
	v_fmac_f32_e32 v2, 0xbc800000, v4
	v_pk_mul_f32 v[4:5], v[2:3], v[2:3]
	v_pk_mul_f32 v[6:7], v[0:1], v[0:1]
	s_nop 0
	v_pk_mov_b32 v[8:9], v[6:7], v[4:5] op_sel:[1,0]
	v_mov_b32_e32 v7, v5
	v_pk_add_f32 v[4:5], v[8:9], v[6:7]
	s_nop 0
	v_add_f32_e32 v4, v4, v5
	s_nop 1
	v_add_f32_dpp v4, v4, v4 quad_perm:[1,0,3,2] row_mask:0xf bank_mask:0xf bound_ctrl:1
	s_nop 1
	v_add_f32_dpp v4, v4, v4 quad_perm:[2,3,0,1] row_mask:0xf bank_mask:0xf bound_ctrl:1
	s_nop 1
	v_add_f32_dpp v4, v4, v4 row_half_mirror row_mask:0xf bank_mask:0xf bound_ctrl:1
	s_nop 1
	v_add_f32_dpp v4, v4, v4 row_mirror row_mask:0xf bank_mask:0xf bound_ctrl:1
	v_fmamk_f32 v4, v4, 0x3c800000, v84
	v_rsq_f32_e32 v4, v4
	s_nop 0
	v_pk_mul_f32 v[8:9], v[2:3], v[4:5] op_sel_hi:[1,0]
	v_pk_mul_f32 v[10:11], v[0:1], v[4:5] op_sel_hi:[1,0]
	ds_read_b128 v[0:3], v59
	ds_read_b128 v[4:7], v59 offset:4096
	s_waitcnt lgkmcnt(0)
	v_pk_fma_f32 v[0:1], v[0:1], v[10:11], v[4:5]
	v_lshl_add_u64 v[4:5], s[74:75], 0, v[34:35]
	v_pk_fma_f32 v[2:3], v[2:3], v[8:9], v[6:7]
	v_add_co_u32_e32 v6, vcc, s11, v4
	s_nop 1
	v_addc_co_u32_e32 v7, vcc, 0, v5, vcc
	v_add_co_u32_e32 v4, vcc, s13, v4
	s_waitcnt vmcnt(53)
	v_mov_b32_e32 v8, v108
	v_mov_b32_e32 v9, v109
	s_nop 0
	v_addc_co_u32_e32 v5, vcc, 0, v5, vcc
	s_waitcnt vmcnt(52)
	v_mov_b32_e32 v4, v110
	v_mov_b32_e32 v5, v111
	v_add_co_u32_e32 v46, vcc, s11, v44
	s_waitcnt vmcnt(51)
	v_mov_b32_e32 v6, v112
	v_mov_b32_e32 v7, v113
	s_nop 0
	v_addc_co_u32_e32 v47, vcc, 0, v45, vcc
	v_add_co_u32_e32 v44, vcc, s13, v44
	v_lshlrev_b32_e32 v10, 16, v8
	v_addc_co_u32_e32 v45, vcc, 0, v45, vcc
	v_and_b32_e32 v11, 0xffff0000, v8
	v_lshlrev_b32_e32 v48, 16, v9
	v_and_b32_e32 v49, 0xffff0000, v9
	v_lshlrev_b32_e32 v50, 16, v6
	v_and_b32_e32 v51, 0xffff0000, v6
	v_lshlrev_b32_e32 v52, 16, v7
	v_and_b32_e32 v53, 0xffff0000, v7
	ds_read_b128 v[6:9], v59 offset:8192
	ds_read_b128 v[40:43], v59 offset:12288
	s_waitcnt vmcnt(50)
	v_mov_b32_e32 v62, v114
	v_mov_b32_e32 v63, v115
	v_lshlrev_b32_e32 v56, 16, v5
	s_waitcnt vmcnt(49)
	v_mov_b32_e32 v44, v116
	v_mov_b32_e32 v45, v117
	v_and_b32_e32 v57, 0xffff0000, v5
	s_waitcnt vmcnt(48)
	v_mov_b32_e32 v46, v118
	v_mov_b32_e32 v47, v119
	v_lshlrev_b32_e32 v54, 16, v4
	v_and_b32_e32 v55, 0xffff0000, v4
	v_lshl_add_u64 v[4:5], s[74:75], 0, v[18:19]
	v_lshl_add_u64 v[18:19], v[18:19], 0, s[46:47]
	v_lshlrev_b32_e32 v61, 16, v62
	v_and_b32_e32 v62, 0xffff0000, v62
	v_lshlrev_b32_e32 v67, 16, v44
	v_and_b32_e32 v44, 0xffff0000, v44
	v_lshlrev_b32_e32 v65, 16, v46
	v_and_b32_e32 v46, 0xffff0000, v46
	v_lshlrev_b32_e32 v66, 16, v47
	v_and_b32_e32 v47, 0xffff0000, v47
	v_lshlrev_b32_e32 v68, 16, v45
	v_and_b32_e32 v45, 0xffff0000, v45
	v_cndmask_b32_e64 v72, v67, 0, s[52:53]
	v_cndmask_b32_e64 v73, v44, 0, s[52:53]
	v_cndmask_b32_e64 v71, v45, 0, s[52:53]
	v_cndmask_b32_e64 v69, v46, 0, s[52:53]
	v_cndmask_b32_e64 v67, v47, 0, s[52:53]
	ds_read_b128 v[44:47], v59 offset:16384
	v_lshlrev_b32_e32 v64, 16, v63
	v_and_b32_e32 v63, 0xffff0000, v63
	v_cndmask_b32_e64 v70, v68, 0, s[52:53]
	v_cndmask_b32_e64 v68, v65, 0, s[52:53]
	v_cndmask_b32_e64 v64, v64, 0, s[52:53]
	v_cndmask_b32_e64 v65, v63, 0, s[52:53]
	v_cndmask_b32_e64 v61, v61, 0, s[52:53]
	v_cndmask_b32_e64 v62, v62, 0, s[52:53]
	v_sub_f32_e32 v63, v62, v11
	v_sub_f32_e32 v62, v61, v10
	v_sub_f32_e32 v65, v65, v49
	v_sub_f32_e32 v64, v64, v48
	s_waitcnt lgkmcnt(0)
	v_pk_fma_f32 v[64:65], v[46:47], v[64:65], v[48:49]
	v_pk_fma_f32 v[62:63], v[44:45], v[62:63], v[10:11]
	ds_read_b128 v[44:47], v59 offset:20480
	v_cndmask_b32_e64 v66, v66, 0, s[52:53]
	v_sub_f32_e32 v67, v67, v53
	v_sub_f32_e32 v66, v66, v52
	v_sub_f32_e32 v69, v69, v51
	v_sub_f32_e32 v68, v68, v50
	s_waitcnt lgkmcnt(0)
	v_pk_fma_f32 v[68:69], v[44:45], v[68:69], v[50:51]
	v_pk_fma_f32 v[66:67], v[46:47], v[66:67], v[52:53]
	ds_read_b128 v[44:47], v59 offset:24576
	v_sub_f32_e32 v71, v71, v57
	v_sub_f32_e32 v70, v70, v56
	v_sub_f32_e32 v73, v73, v55
	v_sub_f32_e32 v72, v72, v54
	s_waitcnt lgkmcnt(0)
	v_pk_fma_f32 v[46:47], v[46:47], v[70:71], v[56:57]
	v_add_co_u32_e32 v70, vcc, s97, v4
	v_pk_fma_f32 v[44:45], v[44:45], v[72:73], v[54:55]
	s_nop 0
	v_addc_co_u32_e32 v71, vcc, 0, v5, vcc
	s_waitcnt vmcnt(47)
	v_mov_b32_e32 v70, v120
	v_mov_b32_e32 v71, v121
	v_lshlrev_b32_e32 v72, 16, v70
	v_and_b32_e32 v73, 0xffff0000, v70
	v_lshlrev_b32_e32 v70, 16, v71
	v_and_b32_e32 v71, 0xffff0000, v71
	v_pk_add_f32 v[70:71], v[70:71], -1.0 op_sel_hi:[1,0]
	v_pk_add_f32 v[72:73], v[72:73], -1.0 op_sel_hi:[1,0]
	v_pk_fma_f32 v[70:71], v[42:43], v[70:71], 1.0 op_sel_hi:[1,1,0]
	v_pk_fma_f32 v[72:73], v[40:41], v[72:73], 1.0 op_sel_hi:[1,1,0]
	v_pk_mul_f32 v[66:67], v[66:67], v[70:71]
	v_pk_mul_f32 v[68:69], v[68:69], v[72:73]
	v_pk_mul_f32 v[64:65], v[64:65], v[66:67]
	v_pk_mul_f32 v[62:63], v[62:63], v[68:69]
	v_pk_mul_f32 v[64:65], v[8:9], v[64:65]
	v_pk_mul_f32 v[62:63], v[6:7], v[62:63]
	s_nop 0
	v_pk_mov_b32 v[66:67], v[62:63], v[64:65] op_sel:[1,0]
	v_mov_b32_e32 v63, v65
	v_pk_add_f32 v[62:63], v[66:67], v[62:63]
	s_nop 0
	v_add_f32_e32 v61, v62, v63
	s_nop 1
	v_add_f32_dpp v61, v61, v61 quad_perm:[1,0,3,2] row_mask:0xf bank_mask:0xf bound_ctrl:1
	s_nop 1
	v_add_f32_dpp v61, v61, v61 quad_perm:[2,3,0,1] row_mask:0xf bank_mask:0xf bound_ctrl:1
	s_nop 1
	v_add_f32_dpp v61, v61, v61 row_half_mirror row_mask:0xf bank_mask:0xf bound_ctrl:1
	s_nop 1
	v_add_f32_dpp v62, v61, v61 row_mirror row_mask:0xf bank_mask:0xf bound_ctrl:1
	v_pk_fma_f32 v[44:45], v[44:45], v[62:63], v[0:1] op_sel_hi:[1,0,1]
	v_lshl_add_u64 v[0:1], s[56:57], 0, v[34:35]
	v_pk_fma_f32 v[46:47], v[46:47], v[62:63], v[2:3] op_sel_hi:[1,0,1]
	v_add_co_u32_e32 v2, vcc, s11, v0
	v_lshl_add_u64 v[34:35], v[34:35], 0, s[48:49]
	s_nop 0
	v_addc_co_u32_e32 v3, vcc, 0, v1, vcc
	v_add_co_u32_e32 v0, vcc, s13, v0
	s_waitcnt vmcnt(46)
	v_mov_b32_e32 v62, v122
	v_mov_b32_e32 v63, v123
	s_nop 0
	v_addc_co_u32_e32 v1, vcc, 0, v1, vcc
	s_waitcnt vmcnt(45)
	v_mov_b32_e32 v0, v124
	v_mov_b32_e32 v1, v125
	v_lshlrev_b32_e32 v61, 16, v62
	s_waitcnt vmcnt(44)
	v_mov_b32_e32 v2, v126
	v_mov_b32_e32 v3, v127
	v_and_b32_e32 v62, 0xffff0000, v62
	v_lshlrev_b32_e32 v67, 16, v0
	v_and_b32_e32 v0, 0xffff0000, v0
	v_lshlrev_b32_e32 v68, 16, v1
	v_and_b32_e32 v1, 0xffff0000, v1
	v_cndmask_b32_e64 v69, v1, 0, s[50:51]
	v_cndmask_b32_e64 v70, v0, 0, s[50:51]
	v_lshlrev_b32_e32 v64, 16, v63
	v_and_b32_e32 v63, 0xffff0000, v63
	v_cndmask_b32_e64 v64, v64, 0, s[50:51]
	v_cndmask_b32_e64 v61, v61, 0, s[50:51]
	v_cndmask_b32_e64 v62, v62, 0, s[50:51]
	v_sub_f32_e32 v64, v64, v48
	v_cndmask_b32_e64 v67, v67, 0, s[50:51]
	v_cndmask_b32_e64 v68, v68, 0, s[50:51]
	v_lshlrev_b32_e32 v65, 16, v2
	v_and_b32_e32 v2, 0xffff0000, v2
	v_lshlrev_b32_e32 v66, 16, v3
	v_and_b32_e32 v3, 0xffff0000, v3
	v_cndmask_b32_e64 v72, v2, 0, s[50:51]
	v_cndmask_b32_e64 v73, v3, 0, s[50:51]
	ds_read_b128 v[0:3], v59 offset:28672
	v_cndmask_b32_e64 v71, v65, 0, s[50:51]
	v_cndmask_b32_e64 v65, v63, 0, s[50:51]
	v_sub_f32_e32 v63, v62, v11
	v_sub_f32_e32 v62, v61, v10
	v_sub_f32_e32 v65, v65, v49
	s_waitcnt lgkmcnt(0)
	v_pk_fma_f32 v[48:49], v[2:3], v[64:65], v[48:49]
	v_pk_fma_f32 v[10:11], v[0:1], v[62:63], v[10:11]
	ds_read_b128 v[0:3], v59 offset:32768
	v_cndmask_b32_e64 v66, v66, 0, s[50:51]
	v_sub_f32_e32 v63, v73, v53
	v_sub_f32_e32 v62, v66, v52
	v_sub_f32_e32 v65, v72, v51
	v_sub_f32_e32 v64, v71, v50
	s_waitcnt lgkmcnt(0)
	v_pk_fma_f32 v[50:51], v[0:1], v[64:65], v[50:51]
	v_pk_fma_f32 v[52:53], v[2:3], v[62:63], v[52:53]
	ds_read_b128 v[0:3], v59 offset:36864
	v_sub_f32_e32 v63, v70, v55
	v_sub_f32_e32 v62, v67, v54
	v_sub_f32_e32 v65, v69, v57
	v_sub_f32_e32 v64, v68, v56
	s_waitcnt lgkmcnt(0)
	v_pk_fma_f32 v[0:1], v[0:1], v[62:63], v[54:55]
	v_add_co_u32_e32 v54, vcc, s70, v4
	v_pk_fma_f32 v[2:3], v[2:3], v[64:65], v[56:57]
	s_nop 0
	v_addc_co_u32_e32 v55, vcc, 0, v5, vcc
	s_waitcnt vmcnt(43)
	v_mov_b32_e32 v54, v128
	v_mov_b32_e32 v55, v129
	v_lshl_add_u64 v[62:63], s[54:55], 0, v[32:33]
	v_lshlrev_b32_e32 v56, 16, v54
	v_and_b32_e32 v57, 0xffff0000, v54
	v_lshlrev_b32_e32 v54, 16, v55
	v_and_b32_e32 v55, 0xffff0000, v55
	v_pk_add_f32 v[54:55], v[54:55], -1.0 op_sel_hi:[1,0]
	v_pk_add_f32 v[56:57], v[56:57], -1.0 op_sel_hi:[1,0]
	v_pk_fma_f32 v[42:43], v[42:43], v[54:55], 1.0 op_sel_hi:[1,1,0]
	v_pk_fma_f32 v[40:41], v[40:41], v[56:57], 1.0 op_sel_hi:[1,1,0]
	v_pk_mul_f32 v[42:43], v[52:53], v[42:43]
	v_pk_mul_f32 v[40:41], v[50:51], v[40:41]
	v_lshl_add_u64 v[52:53], s[74:75], 0, v[26:27]
	v_pk_mul_f32 v[10:11], v[10:11], v[40:41]
	v_pk_mul_f32 v[40:41], v[48:49], v[42:43]
	v_pk_mul_f32 v[6:7], v[6:7], v[10:11]
	v_pk_mul_f32 v[8:9], v[8:9], v[40:41]
	v_lshl_add_u64 v[26:27], v[26:27], 0, s[46:47]
	v_pk_mov_b32 v[10:11], v[6:7], v[8:9] op_sel:[1,0]
	v_add_co_u32_e32 v8, vcc, s2, v4
	v_mov_b32_e32 v7, v9
	s_nop 0
	v_addc_co_u32_e32 v9, vcc, 0, v5, vcc
	s_waitcnt vmcnt(42)
	v_mov_b32_e32 v4, v130
	v_mov_b32_e32 v5, v131
	v_pk_add_f32 v[6:7], v[10:11], v[6:7]
	s_nop 0
	v_add_f32_e32 v6, v6, v7
	s_nop 1
	v_add_f32_dpp v6, v6, v6 quad_perm:[1,0,3,2] row_mask:0xf bank_mask:0xf bound_ctrl:1
	s_nop 1
	v_add_f32_dpp v6, v6, v6 quad_perm:[2,3,0,1] row_mask:0xf bank_mask:0xf bound_ctrl:1
	s_nop 1
	v_add_f32_dpp v6, v6, v6 row_half_mirror row_mask:0xf bank_mask:0xf bound_ctrl:1
	s_nop 1
	v_add_f32_dpp v6, v6, v6 row_mirror row_mask:0xf bank_mask:0xf bound_ctrl:1
	v_pk_fma_f32 v[0:1], v[0:1], v[6:7], v[44:45] op_sel_hi:[1,0,1]
	v_pk_fma_f32 v[2:3], v[2:3], v[6:7], v[46:47] op_sel_hi:[1,0,1]
	v_lshlrev_b32_e32 v6, 16, v4
	v_and_b32_e32 v7, 0xffff0000, v4
	v_lshlrev_b32_e32 v4, 16, v5
	v_and_b32_e32 v5, 0xffff0000, v5
	v_pk_mul_f32 v[2:3], v[2:3], v[4:5]
	v_pk_mul_f32 v[0:1], v[0:1], v[6:7]
	ds_write_b128 v60, v[0:3]
	v_pk_mul_f32 v[2:3], v[2:3], v[2:3]
	v_pk_mul_f32 v[0:1], v[0:1], v[0:1]
	s_nop 0
	v_pk_mov_b32 v[4:5], v[0:1], v[2:3] op_sel:[1,0]
	v_mov_b32_e32 v1, v3
	v_pk_add_f32 v[0:1], v[4:5], v[0:1]
	s_nop 0
	v_pk_add_f32 v[10:11], v[0:1], v[0:1] op_sel:[0,1] op_sel_hi:[1,0]
	s_waitcnt vmcnt(41)
	v_mov_b32_e32 v0, v132
	v_mov_b32_e32 v1, v133
	v_mov_b32_e32 v2, v134
	v_mov_b32_e32 v3, v135
	s_waitcnt vmcnt(40)
	v_mov_b32_e32 v4, v136
	v_mov_b32_e32 v5, v137
	v_mov_b32_e32 v6, v138
	v_mov_b32_e32 v7, v139
	v_pk_add_f32 v[2:3], v[2:3], v[6:7]
	v_pk_add_f32 v[4:5], v[0:1], v[4:5]
	v_mov_b32_e32 v7, v3
	v_pk_mov_b32 v[0:1], v[4:5], v[2:3] op_sel:[1,0]
	v_mov_b32_e32 v6, v4
	v_pk_add_f32 v[0:1], v[0:1], v[6:7]
	s_nop 0
	v_add_f32_e32 v0, v0, v1
	s_nop 1
	v_add_f32_dpp v0, v0, v0 quad_perm:[1,0,3,2] row_mask:0xf bank_mask:0xf bound_ctrl:1
	s_nop 1
	v_add_f32_dpp v0, v0, v0 quad_perm:[2,3,0,1] row_mask:0xf bank_mask:0xf bound_ctrl:1
	s_nop 1
	v_add_f32_dpp v0, v0, v0 row_half_mirror row_mask:0xf bank_mask:0xf bound_ctrl:1
	s_nop 1
	v_add_f32_dpp v0, v0, v0 row_mirror row_mask:0xf bank_mask:0xf bound_ctrl:1
	v_fmamk_f32 v5, v0, 0xbc800000, v5
	v_fmac_f32_e32 v4, 0xbc800000, v0
	v_fmamk_f32 v3, v0, 0xbc800000, v3
	v_fmac_f32_e32 v2, 0xbc800000, v0
	v_pk_mul_f32 v[0:1], v[2:3], v[2:3]
	v_pk_mul_f32 v[6:7], v[4:5], v[4:5]
	s_nop 0
	v_pk_mov_b32 v[40:41], v[6:7], v[0:1] op_sel:[1,0]
	v_mov_b32_e32 v7, v1
	v_pk_add_f32 v[0:1], v[40:41], v[6:7]
	s_nop 0
	v_add_f32_e32 v0, v0, v1
	s_nop 1
	v_add_f32_dpp v0, v0, v0 quad_perm:[1,0,3,2] row_mask:0xf bank_mask:0xf bound_ctrl:1
	s_nop 1
	v_add_f32_dpp v0, v0, v0 quad_perm:[2,3,0,1] row_mask:0xf bank_mask:0xf bound_ctrl:1
	s_nop 1
	v_add_f32_dpp v0, v0, v0 row_half_mirror row_mask:0xf bank_mask:0xf bound_ctrl:1
	s_nop 1
	v_add_f32_dpp v0, v0, v0 row_mirror row_mask:0xf bank_mask:0xf bound_ctrl:1
	v_fmamk_f32 v0, v0, 0x3c800000, v84
	v_rsq_f32_e32 v6, v0
	s_nop 0
	v_pk_mul_f32 v[0:1], v[2:3], v[6:7] op_sel_hi:[1,0]
	v_pk_mul_f32 v[2:3], v[4:5], v[6:7] op_sel_hi:[1,0]
	ds_read_b128 v[4:7], v59 offset:1024
	ds_read_b128 v[40:43], v59 offset:5120
	s_waitcnt lgkmcnt(0)
	v_pk_fma_f32 v[56:57], v[6:7], v[0:1], v[42:43]
	v_lshl_add_u64 v[0:1], s[74:75], 0, v[32:33]
	v_pk_fma_f32 v[54:55], v[4:5], v[2:3], v[40:41]
	v_add_co_u32_e32 v2, vcc, s11, v0
	s_nop 1
	v_addc_co_u32_e32 v3, vcc, 0, v1, vcc
	v_add_co_u32_e32 v0, vcc, s13, v0
	s_waitcnt vmcnt(39)
	v_mov_b32_e32 v4, v140
	v_mov_b32_e32 v5, v141
	s_nop 0
	v_addc_co_u32_e32 v1, vcc, 0, v1, vcc
	s_waitcnt vmcnt(38)
	v_mov_b32_e32 v0, v142
	v_mov_b32_e32 v1, v143
	v_add_co_u32_e32 v64, vcc, s11, v62
	s_waitcnt vmcnt(37)
	v_mov_b32_e32 v2, v144
	v_mov_b32_e32 v3, v145
	s_nop 0
	v_addc_co_u32_e32 v65, vcc, 0, v63, vcc
	v_add_co_u32_e32 v62, vcc, s13, v62
	v_lshlrev_b32_e32 v48, 16, v4
	v_addc_co_u32_e32 v63, vcc, 0, v63, vcc
	v_and_b32_e32 v49, 0xffff0000, v4
	v_lshlrev_b32_e32 v50, 16, v5
	v_and_b32_e32 v51, 0xffff0000, v5
	v_lshlrev_b32_e32 v44, 16, v2
	v_and_b32_e32 v45, 0xffff0000, v2
	v_lshlrev_b32_e32 v46, 16, v3
	v_and_b32_e32 v47, 0xffff0000, v3
	v_lshlrev_b32_e32 v40, 16, v0
	v_and_b32_e32 v41, 0xffff0000, v0
	v_lshlrev_b32_e32 v42, 16, v1
	v_and_b32_e32 v43, 0xffff0000, v1
	ds_read_b128 v[0:3], v59 offset:9216
	ds_read_b128 v[4:7], v59 offset:13312
	s_waitcnt vmcnt(36)
	v_mov_b32_e32 v66, v146
	v_mov_b32_e32 v67, v147
	s_nop 0
	s_waitcnt vmcnt(35)
	v_mov_b32_e32 v62, v148
	v_mov_b32_e32 v63, v149
	v_lshlrev_b32_e32 v11, 16, v66
	s_waitcnt vmcnt(34)
	v_mov_b32_e32 v64, v150
	v_mov_b32_e32 v65, v151
	v_lshlrev_b32_e32 v70, 16, v62
	v_and_b32_e32 v62, 0xffff0000, v62
	v_lshlrev_b32_e32 v71, 16, v63
	v_and_b32_e32 v63, 0xffff0000, v63
	v_cndmask_b32_e64 v77, v62, 0, s[52:53]
	v_cndmask_b32_e64 v74, v71, 0, s[52:53]
	v_cndmask_b32_e64 v75, v63, 0, s[52:53]
	v_and_b32_e32 v61, 0xffff0000, v66
	v_lshlrev_b32_e32 v66, 16, v67
	v_and_b32_e32 v67, 0xffff0000, v67
	v_cndmask_b32_e64 v76, v70, 0, s[52:53]
	v_cndmask_b32_e64 v11, v11, 0, s[52:53]
	v_cndmask_b32_e64 v61, v61, 0, s[52:53]
	v_sub_f32_e32 v75, v75, v43
	v_sub_f32_e32 v74, v74, v42
	v_sub_f32_e32 v77, v77, v41
	v_sub_f32_e32 v76, v76, v40
	v_lshlrev_b32_e32 v68, 16, v64
	v_and_b32_e32 v64, 0xffff0000, v64
	v_lshlrev_b32_e32 v69, 16, v65
	v_and_b32_e32 v65, 0xffff0000, v65
	v_cndmask_b32_e64 v73, v64, 0, s[52:53]
	v_cndmask_b32_e64 v71, v65, 0, s[52:53]
	ds_read_b128 v[62:65], v59 offset:17408
	v_cndmask_b32_e64 v72, v68, 0, s[52:53]
	v_cndmask_b32_e64 v70, v69, 0, s[52:53]
	v_cndmask_b32_e64 v68, v66, 0, s[52:53]
	v_cndmask_b32_e64 v69, v67, 0, s[52:53]
	v_sub_f32_e32 v67, v61, v49
	v_sub_f32_e32 v66, v11, v48
	v_sub_f32_e32 v69, v69, v51
	v_sub_f32_e32 v68, v68, v50
	s_waitcnt lgkmcnt(0)
	v_pk_fma_f32 v[68:69], v[64:65], v[68:69], v[50:51]
	v_pk_fma_f32 v[66:67], v[62:63], v[66:67], v[48:49]
	ds_read_b128 v[62:65], v59 offset:21504
	v_sub_f32_e32 v71, v71, v47
	v_sub_f32_e32 v70, v70, v46
	v_sub_f32_e32 v73, v73, v45
	v_sub_f32_e32 v72, v72, v44
	s_waitcnt lgkmcnt(0)
	v_pk_fma_f32 v[72:73], v[62:63], v[72:73], v[44:45]
	v_pk_fma_f32 v[70:71], v[64:65], v[70:71], v[46:47]
	ds_read_b128 v[62:65], v59 offset:25600
	s_waitcnt lgkmcnt(0)
	v_pk_fma_f32 v[64:65], v[64:65], v[74:75], v[42:43]
	v_add_co_u32_e32 v74, vcc, s97, v52
	v_pk_fma_f32 v[62:63], v[62:63], v[76:77], v[40:41]
	s_nop 0
	v_addc_co_u32_e32 v75, vcc, 0, v53, vcc
	s_waitcnt vmcnt(33)
	v_mov_b32_e32 v74, v152
	v_mov_b32_e32 v75, v153
	v_lshlrev_b32_e32 v76, 16, v74
	v_and_b32_e32 v77, 0xffff0000, v74
	v_lshlrev_b32_e32 v74, 16, v75
	v_and_b32_e32 v75, 0xffff0000, v75
	v_pk_add_f32 v[74:75], v[74:75], -1.0 op_sel_hi:[1,0]
	v_pk_add_f32 v[76:77], v[76:77], -1.0 op_sel_hi:[1,0]
	v_pk_fma_f32 v[74:75], v[6:7], v[74:75], 1.0 op_sel_hi:[1,1,0]
	v_pk_fma_f32 v[76:77], v[4:5], v[76:77], 1.0 op_sel_hi:[1,1,0]
	v_pk_mul_f32 v[70:71], v[70:71], v[74:75]
	v_pk_mul_f32 v[72:73], v[72:73], v[76:77]
	v_pk_mul_f32 v[68:69], v[68:69], v[70:71]
	v_pk_mul_f32 v[66:67], v[66:67], v[72:73]
	v_pk_mul_f32 v[68:69], v[2:3], v[68:69]
	v_pk_mul_f32 v[66:67], v[0:1], v[66:67]
	s_nop 0
	v_pk_mov_b32 v[70:71], v[66:67], v[68:69] op_sel:[1,0]
	v_mov_b32_e32 v67, v69
	v_pk_add_f32 v[66:67], v[70:71], v[66:67]
	s_nop 0
	v_add_f32_e32 v11, v66, v67
	s_nop 1
	v_add_f32_dpp v11, v11, v11 quad_perm:[1,0,3,2] row_mask:0xf bank_mask:0xf bound_ctrl:1
	s_nop 1
	v_add_f32_dpp v11, v11, v11 quad_perm:[2,3,0,1] row_mask:0xf bank_mask:0xf bound_ctrl:1
	s_nop 1
	v_add_f32_dpp v11, v11, v11 row_half_mirror row_mask:0xf bank_mask:0xf bound_ctrl:1
	s_nop 1
	v_add_f32_dpp v66, v11, v11 row_mirror row_mask:0xf bank_mask:0xf bound_ctrl:1
	v_pk_fma_f32 v[62:63], v[62:63], v[66:67], v[54:55] op_sel_hi:[1,0,1]
	v_lshl_add_u64 v[54:55], s[56:57], 0, v[32:33]
	v_pk_fma_f32 v[64:65], v[64:65], v[66:67], v[56:57] op_sel_hi:[1,0,1]
	v_add_co_u32_e32 v56, vcc, s11, v54
	v_lshl_add_u64 v[32:33], v[32:33], 0, s[48:49]
	s_nop 0
	v_addc_co_u32_e32 v57, vcc, 0, v55, vcc
	v_add_co_u32_e32 v54, vcc, s13, v54
	s_waitcnt vmcnt(32)
	v_mov_b32_e32 v66, v154
	v_mov_b32_e32 v67, v155
	s_nop 0
	v_addc_co_u32_e32 v55, vcc, 0, v55, vcc
	s_waitcnt vmcnt(31)
	v_mov_b32_e32 v54, v156
	v_mov_b32_e32 v55, v157
	v_lshlrev_b32_e32 v11, 16, v66
	s_waitcnt vmcnt(30)
	v_mov_b32_e32 v56, v158
	v_mov_b32_e32 v57, v159
	v_and_b32_e32 v61, 0xffff0000, v66
	v_lshlrev_b32_e32 v70, 16, v54
	v_and_b32_e32 v54, 0xffff0000, v54
	v_lshlrev_b32_e32 v71, 16, v55
	v_and_b32_e32 v55, 0xffff0000, v55
	v_cndmask_b32_e64 v72, v55, 0, s[50:51]
	v_cndmask_b32_e64 v73, v54, 0, s[50:51]
	v_lshlrev_b32_e32 v66, 16, v67
	v_and_b32_e32 v67, 0xffff0000, v67
	v_cndmask_b32_e64 v11, v11, 0, s[50:51]
	v_cndmask_b32_e64 v61, v61, 0, s[50:51]
	v_cndmask_b32_e64 v70, v70, 0, s[50:51]
	v_cndmask_b32_e64 v71, v71, 0, s[50:51]
	v_lshlrev_b32_e32 v68, 16, v56
	v_and_b32_e32 v56, 0xffff0000, v56
	v_lshlrev_b32_e32 v69, 16, v57
	v_and_b32_e32 v57, 0xffff0000, v57
	v_cndmask_b32_e64 v75, v56, 0, s[50:51]
	v_cndmask_b32_e64 v77, v57, 0, s[50:51]
	ds_read_b128 v[54:57], v59 offset:29696
	v_cndmask_b32_e64 v74, v68, 0, s[50:51]
	v_cndmask_b32_e64 v76, v69, 0, s[50:51]
	v_cndmask_b32_e64 v68, v66, 0, s[50:51]
	v_cndmask_b32_e64 v69, v67, 0, s[50:51]
	v_sub_f32_e32 v67, v61, v49
	v_sub_f32_e32 v66, v11, v48
	v_sub_f32_e32 v69, v69, v51
	v_sub_f32_e32 v68, v68, v50
	s_waitcnt lgkmcnt(0)
	v_pk_fma_f32 v[56:57], v[56:57], v[68:69], v[50:51]
	v_pk_fma_f32 v[54:55], v[54:55], v[66:67], v[48:49]
	ds_read_b128 v[48:51], v59 offset:33792
	v_sub_f32_e32 v67, v77, v47
	v_sub_f32_e32 v66, v76, v46
	v_sub_f32_e32 v69, v75, v45
	v_sub_f32_e32 v68, v74, v44
	s_waitcnt lgkmcnt(0)
	v_pk_fma_f32 v[48:49], v[48:49], v[68:69], v[44:45]
	v_pk_fma_f32 v[50:51], v[50:51], v[66:67], v[46:47]
	ds_read_b128 v[44:47], v59 offset:37888
	v_sub_f32_e32 v67, v73, v41
	v_sub_f32_e32 v66, v70, v40
	v_sub_f32_e32 v69, v72, v43
	v_sub_f32_e32 v68, v71, v42
	s_waitcnt lgkmcnt(0)
	v_pk_fma_f32 v[40:41], v[44:45], v[66:67], v[40:41]
	v_add_co_u32_e32 v44, vcc, s70, v52
	v_pk_fma_f32 v[42:43], v[46:47], v[68:69], v[42:43]
	s_nop 0
	v_addc_co_u32_e32 v45, vcc, 0, v53, vcc
	s_waitcnt vmcnt(29)
	v_mov_b32_e32 v44, v160
	v_mov_b32_e32 v45, v161
	v_lshl_add_u64 v[66:67], s[74:75], 0, v[24:25]
	v_lshl_add_u64 v[24:25], v[24:25], 0, s[46:47]
	v_lshlrev_b32_e32 v46, 16, v44
	v_and_b32_e32 v47, 0xffff0000, v44
	v_lshlrev_b32_e32 v44, 16, v45
	v_and_b32_e32 v45, 0xffff0000, v45
	v_pk_add_f32 v[44:45], v[44:45], -1.0 op_sel_hi:[1,0]
	v_pk_add_f32 v[46:47], v[46:47], -1.0 op_sel_hi:[1,0]
	v_pk_fma_f32 v[6:7], v[6:7], v[44:45], 1.0 op_sel_hi:[1,1,0]
	v_pk_fma_f32 v[4:5], v[4:5], v[46:47], 1.0 op_sel_hi:[1,1,0]
	v_pk_mul_f32 v[6:7], v[50:51], v[6:7]
	v_pk_mul_f32 v[4:5], v[48:49], v[4:5]
	v_pk_mul_f32 v[6:7], v[56:57], v[6:7]
	v_pk_mul_f32 v[4:5], v[54:55], v[4:5]
	v_pk_mul_f32 v[2:3], v[2:3], v[6:7]
	v_pk_mul_f32 v[0:1], v[0:1], v[4:5]
	v_lshl_add_u64 v[46:47], s[54:55], 0, v[30:31]
	v_pk_mov_b32 v[4:5], v[0:1], v[2:3] op_sel:[1,0]
	v_mov_b32_e32 v1, v3
	s_waitcnt vmcnt(28)
	v_mov_b32_e32 v2, v162
	v_mov_b32_e32 v3, v163
	v_pk_add_f32 v[0:1], v[4:5], v[0:1]
	v_lshlrev_b32_e32 v6, 16, v2
	v_add_f32_e32 v0, v0, v1
	v_and_b32_e32 v7, 0xffff0000, v2
	v_lshlrev_b32_e32 v2, 16, v3
	v_add_f32_dpp v0, v0, v0 quad_perm:[1,0,3,2] row_mask:0xf bank_mask:0xf bound_ctrl:1
	v_and_b32_e32 v3, 0xffff0000, v3
	s_nop 0
	v_add_f32_dpp v0, v0, v0 quad_perm:[2,3,0,1] row_mask:0xf bank_mask:0xf bound_ctrl:1
	s_nop 1
	v_add_f32_dpp v0, v0, v0 row_half_mirror row_mask:0xf bank_mask:0xf bound_ctrl:1
	s_nop 1
	v_add_f32_dpp v0, v0, v0 row_mirror row_mask:0xf bank_mask:0xf bound_ctrl:1
	v_pk_fma_f32 v[4:5], v[40:41], v[0:1], v[62:63] op_sel_hi:[1,0,1]
	v_pk_fma_f32 v[0:1], v[42:43], v[0:1], v[64:65] op_sel_hi:[1,0,1]
	s_nop 0
	v_pk_mul_f32 v[2:3], v[0:1], v[2:3]
	v_pk_mul_f32 v[0:1], v[4:5], v[6:7]
	ds_write_b128 v60, v[0:3] offset:1024
	v_pk_mul_f32 v[2:3], v[2:3], v[2:3]
	v_pk_mul_f32 v[0:1], v[0:1], v[0:1]
	s_nop 0
	v_pk_mov_b32 v[4:5], v[0:1], v[2:3] op_sel:[1,0]
	v_mov_b32_e32 v1, v3
	v_pk_add_f32 v[0:1], v[4:5], v[0:1]
	s_nop 0
	v_pk_add_f32 v[40:41], v[0:1], v[0:1] op_sel:[0,1] op_sel_hi:[1,0]
	s_waitcnt vmcnt(27)
	v_mov_b32_e32 v0, v164
	v_mov_b32_e32 v1, v165
	v_mov_b32_e32 v2, v166
	v_mov_b32_e32 v3, v167
	s_waitcnt vmcnt(26)
	v_mov_b32_e32 v4, v168
	v_mov_b32_e32 v5, v169
	v_mov_b32_e32 v6, v170
	v_mov_b32_e32 v7, v171
	v_pk_add_f32 v[2:3], v[2:3], v[6:7]
	v_pk_add_f32 v[0:1], v[0:1], v[4:5]
	v_mov_b32_e32 v7, v3
	v_pk_mov_b32 v[4:5], v[0:1], v[2:3] op_sel:[1,0]
	v_mov_b32_e32 v6, v0
	v_pk_add_f32 v[4:5], v[4:5], v[6:7]
	s_nop 0
	v_add_f32_e32 v4, v4, v5
	s_nop 1
	v_add_f32_dpp v4, v4, v4 quad_perm:[1,0,3,2] row_mask:0xf bank_mask:0xf bound_ctrl:1
	s_nop 1
	v_add_f32_dpp v4, v4, v4 quad_perm:[2,3,0,1] row_mask:0xf bank_mask:0xf bound_ctrl:1
	s_nop 1
	v_add_f32_dpp v4, v4, v4 row_half_mirror row_mask:0xf bank_mask:0xf bound_ctrl:1
	s_nop 1
	v_add_f32_dpp v4, v4, v4 row_mirror row_mask:0xf bank_mask:0xf bound_ctrl:1
	v_fmamk_f32 v1, v4, 0xbc800000, v1
	v_fmac_f32_e32 v0, 0xbc800000, v4
	v_fmamk_f32 v3, v4, 0xbc800000, v3
	v_fmac_f32_e32 v2, 0xbc800000, v4
	v_pk_mul_f32 v[4:5], v[2:3], v[2:3]
	v_pk_mul_f32 v[6:7], v[0:1], v[0:1]
	s_nop 0
	v_pk_mov_b32 v[42:43], v[6:7], v[4:5] op_sel:[1,0]
	v_mov_b32_e32 v7, v5
	v_pk_add_f32 v[4:5], v[42:43], v[6:7]
	s_nop 0
	v_add_f32_e32 v4, v4, v5
	s_nop 1
	v_add_f32_dpp v4, v4, v4 quad_perm:[1,0,3,2] row_mask:0xf bank_mask:0xf bound_ctrl:1
	s_nop 1
	v_add_f32_dpp v4, v4, v4 quad_perm:[2,3,0,1] row_mask:0xf bank_mask:0xf bound_ctrl:1
	s_nop 1
	v_add_f32_dpp v4, v4, v4 row_half_mirror row_mask:0xf bank_mask:0xf bound_ctrl:1
	s_nop 1
	v_add_f32_dpp v4, v4, v4 row_mirror row_mask:0xf bank_mask:0xf bound_ctrl:1
	v_fmamk_f32 v4, v4, 0x3c800000, v84
	v_rsq_f32_e32 v4, v4
	s_nop 0
	v_pk_mul_f32 v[42:43], v[2:3], v[4:5] op_sel_hi:[1,0]
	v_pk_mul_f32 v[44:45], v[0:1], v[4:5] op_sel_hi:[1,0]
	ds_read_b128 v[0:3], v59 offset:2048
	ds_read_b128 v[4:7], v59 offset:6144
	s_waitcnt lgkmcnt(0)
	v_pk_fma_f32 v[0:1], v[0:1], v[44:45], v[4:5]
	v_lshl_add_u64 v[4:5], s[74:75], 0, v[30:31]
	v_pk_fma_f32 v[2:3], v[2:3], v[42:43], v[6:7]
	v_add_co_u32_e32 v6, vcc, s11, v4
	s_nop 1
	v_addc_co_u32_e32 v7, vcc, 0, v5, vcc
	v_add_co_u32_e32 v4, vcc, s13, v4
	s_waitcnt vmcnt(25)
	v_mov_b32_e32 v42, v172
	v_mov_b32_e32 v43, v173
	s_nop 0
	v_addc_co_u32_e32 v5, vcc, 0, v5, vcc
	s_waitcnt vmcnt(24)
	v_mov_b32_e32 v4, v174
	v_mov_b32_e32 v5, v175
	v_add_co_u32_e32 v48, vcc, s11, v46
	s_waitcnt vmcnt(23)
	v_mov_b32_e32 v6, v176
	v_mov_b32_e32 v7, v177
	s_nop 0
	v_addc_co_u32_e32 v49, vcc, 0, v47, vcc
	v_add_co_u32_e32 v46, vcc, s13, v46
	v_lshlrev_b32_e32 v50, 16, v42
	v_addc_co_u32_e32 v47, vcc, 0, v47, vcc
	v_and_b32_e32 v51, 0xffff0000, v42
	v_lshlrev_b32_e32 v52, 16, v43
	v_and_b32_e32 v53, 0xffff0000, v43
	v_lshlrev_b32_e32 v54, 16, v6
	v_and_b32_e32 v55, 0xffff0000, v6
	v_lshlrev_b32_e32 v56, 16, v7
	v_and_b32_e32 v57, 0xffff0000, v7
	v_lshlrev_b32_e32 v62, 16, v4
	v_and_b32_e32 v63, 0xffff0000, v4
	v_lshlrev_b32_e32 v64, 16, v5
	v_and_b32_e32 v65, 0xffff0000, v5
	ds_read_b128 v[4:7], v59 offset:10240
	ds_read_b128 v[42:45], v59 offset:14336
	s_waitcnt vmcnt(22)
	v_mov_b32_e32 v68, v178
	v_mov_b32_e32 v69, v179
	s_nop 0
	s_waitcnt vmcnt(21)
	v_mov_b32_e32 v46, v180
	v_mov_b32_e32 v47, v181
	v_lshlrev_b32_e32 v11, 16, v68
	s_waitcnt vmcnt(20)
	v_mov_b32_e32 v48, v182
	v_mov_b32_e32 v49, v183
	v_and_b32_e32 v41, 0xffff0000, v68
	v_lshlrev_b32_e32 v61, 16, v69
	v_and_b32_e32 v68, 0xffff0000, v69
	v_lshlrev_b32_e32 v71, 16, v46
	v_and_b32_e32 v46, 0xffff0000, v46
	v_lshlrev_b32_e32 v72, 16, v47
	v_and_b32_e32 v47, 0xffff0000, v47
	v_cndmask_b32_e64 v79, v46, 0, s[52:53]
	v_cndmask_b32_e64 v77, v47, 0, s[52:53]
	v_cndmask_b32_e64 v76, v72, 0, s[52:53]
	v_cndmask_b32_e64 v61, v61, 0, s[52:53]
	v_cndmask_b32_e64 v11, v11, 0, s[52:53]
	v_cndmask_b32_e64 v41, v41, 0, s[52:53]
	v_cndmask_b32_e64 v78, v71, 0, s[52:53]
	v_sub_f32_e32 v77, v77, v65
	v_sub_f32_e32 v76, v76, v64
	v_sub_f32_e32 v79, v79, v63
	v_sub_f32_e32 v78, v78, v62
	v_lshlrev_b32_e32 v69, 16, v48
	v_and_b32_e32 v48, 0xffff0000, v48
	v_lshlrev_b32_e32 v70, 16, v49
	v_and_b32_e32 v49, 0xffff0000, v49
	v_cndmask_b32_e64 v75, v48, 0, s[52:53]
	v_cndmask_b32_e64 v73, v49, 0, s[52:53]
	ds_read_b128 v[46:49], v59 offset:18432
	v_cndmask_b32_e64 v72, v70, 0, s[52:53]
	v_cndmask_b32_e64 v70, v68, 0, s[52:53]
	v_cndmask_b32_e64 v74, v69, 0, s[52:53]
	v_sub_f32_e32 v69, v41, v51
	v_sub_f32_e32 v68, v11, v50
	v_sub_f32_e32 v71, v70, v53
	v_sub_f32_e32 v70, v61, v52
	s_waitcnt lgkmcnt(0)
	v_pk_fma_f32 v[70:71], v[48:49], v[70:71], v[52:53]
	v_pk_fma_f32 v[68:69], v[46:47], v[68:69], v[50:51]
	ds_read_b128 v[46:49], v59 offset:22528
	v_sub_f32_e32 v73, v73, v57
	v_sub_f32_e32 v72, v72, v56
	v_sub_f32_e32 v75, v75, v55
	v_sub_f32_e32 v74, v74, v54
	s_waitcnt lgkmcnt(0)
	v_pk_fma_f32 v[74:75], v[46:47], v[74:75], v[54:55]
	v_pk_fma_f32 v[72:73], v[48:49], v[72:73], v[56:57]
	ds_read_b128 v[46:49], v59 offset:26624
	s_waitcnt lgkmcnt(0)
	v_pk_fma_f32 v[48:49], v[48:49], v[76:77], v[64:65]
	v_add_co_u32_e32 v76, vcc, s97, v66
	v_pk_fma_f32 v[46:47], v[46:47], v[78:79], v[62:63]
	s_nop 0
	v_addc_co_u32_e32 v77, vcc, 0, v67, vcc
	s_waitcnt vmcnt(19)
	v_mov_b32_e32 v76, v184
	v_mov_b32_e32 v77, v185
	v_lshlrev_b32_e32 v78, 16, v76
	v_and_b32_e32 v79, 0xffff0000, v76
	v_lshlrev_b32_e32 v76, 16, v77
	v_and_b32_e32 v77, 0xffff0000, v77
	v_pk_add_f32 v[76:77], v[76:77], -1.0 op_sel_hi:[1,0]
	v_pk_add_f32 v[78:79], v[78:79], -1.0 op_sel_hi:[1,0]
	v_pk_fma_f32 v[76:77], v[44:45], v[76:77], 1.0 op_sel_hi:[1,1,0]
	v_pk_fma_f32 v[78:79], v[42:43], v[78:79], 1.0 op_sel_hi:[1,1,0]
	v_pk_mul_f32 v[72:73], v[72:73], v[76:77]
	v_pk_mul_f32 v[74:75], v[74:75], v[78:79]
	v_pk_mul_f32 v[70:71], v[70:71], v[72:73]
	v_pk_mul_f32 v[68:69], v[68:69], v[74:75]
	v_pk_mul_f32 v[70:71], v[6:7], v[70:71]
	v_pk_mul_f32 v[68:69], v[4:5], v[68:69]
	s_nop 0
	v_pk_mov_b32 v[72:73], v[68:69], v[70:71] op_sel:[1,0]
	v_mov_b32_e32 v69, v71
	v_pk_add_f32 v[68:69], v[72:73], v[68:69]
	s_nop 0
	v_add_f32_e32 v11, v68, v69
	s_nop 1
	v_add_f32_dpp v11, v11, v11 quad_perm:[1,0,3,2] row_mask:0xf bank_mask:0xf bound_ctrl:1
	s_nop 1
	v_add_f32_dpp v11, v11, v11 quad_perm:[2,3,0,1] row_mask:0xf bank_mask:0xf bound_ctrl:1
	s_nop 1
	v_add_f32_dpp v11, v11, v11 row_half_mirror row_mask:0xf bank_mask:0xf bound_ctrl:1
	s_nop 1
	v_add_f32_dpp v68, v11, v11 row_mirror row_mask:0xf bank_mask:0xf bound_ctrl:1
	v_pk_fma_f32 v[46:47], v[46:47], v[68:69], v[0:1] op_sel_hi:[1,0,1]
	v_lshl_add_u64 v[0:1], s[56:57], 0, v[30:31]
	v_pk_fma_f32 v[48:49], v[48:49], v[68:69], v[2:3] op_sel_hi:[1,0,1]
	v_add_co_u32_e32 v2, vcc, s11, v0
	v_lshl_add_u64 v[30:31], v[30:31], 0, s[48:49]
	s_nop 0
	v_addc_co_u32_e32 v3, vcc, 0, v1, vcc
	v_add_co_u32_e32 v0, vcc, s13, v0
	s_waitcnt vmcnt(18)
	v_mov_b32_e32 v68, v186
	v_mov_b32_e32 v69, v187
	s_nop 0
	v_addc_co_u32_e32 v1, vcc, 0, v1, vcc
	s_waitcnt vmcnt(17)
	v_mov_b32_e32 v0, v188
	v_mov_b32_e32 v1, v189
	v_lshlrev_b32_e32 v11, 16, v68
	s_waitcnt vmcnt(16)
	v_mov_b32_e32 v2, v190
	v_mov_b32_e32 v3, v191
	v_and_b32_e32 v41, 0xffff0000, v68
	v_lshlrev_b32_e32 v61, 16, v69
	v_and_b32_e32 v68, 0xffff0000, v69
	v_lshlrev_b32_e32 v71, 16, v0
	v_and_b32_e32 v0, 0xffff0000, v0
	v_lshlrev_b32_e32 v72, 16, v1
	v_and_b32_e32 v1, 0xffff0000, v1
	v_cndmask_b32_e64 v73, v1, 0, s[50:51]
	v_cndmask_b32_e64 v75, v0, 0, s[50:51]
	v_cndmask_b32_e64 v61, v61, 0, s[50:51]
	v_cndmask_b32_e64 v11, v11, 0, s[50:51]
	v_cndmask_b32_e64 v41, v41, 0, s[50:51]
	v_cndmask_b32_e64 v74, v71, 0, s[50:51]
	v_cndmask_b32_e64 v72, v72, 0, s[50:51]
	v_lshlrev_b32_e32 v69, 16, v2
	v_and_b32_e32 v2, 0xffff0000, v2
	v_lshlrev_b32_e32 v70, 16, v3
	v_and_b32_e32 v3, 0xffff0000, v3
	v_cndmask_b32_e64 v77, v2, 0, s[50:51]
	v_cndmask_b32_e64 v79, v3, 0, s[50:51]
	ds_read_b128 v[0:3], v59 offset:30720
	v_cndmask_b32_e64 v78, v70, 0, s[50:51]
	v_cndmask_b32_e64 v70, v68, 0, s[50:51]
	v_cndmask_b32_e64 v76, v69, 0, s[50:51]
	v_sub_f32_e32 v69, v41, v51
	v_sub_f32_e32 v68, v11, v50
	v_sub_f32_e32 v71, v70, v53
	v_sub_f32_e32 v70, v61, v52
	s_waitcnt lgkmcnt(0)
	v_pk_fma_f32 v[52:53], v[2:3], v[70:71], v[52:53]
	v_pk_fma_f32 v[50:51], v[0:1], v[68:69], v[50:51]
	ds_read_b128 v[0:3], v59 offset:34816
	v_sub_f32_e32 v69, v79, v57
	v_sub_f32_e32 v68, v78, v56
	v_sub_f32_e32 v71, v77, v55
	v_sub_f32_e32 v70, v76, v54
	s_waitcnt lgkmcnt(0)
	v_pk_fma_f32 v[54:55], v[0:1], v[70:71], v[54:55]
	v_pk_fma_f32 v[56:57], v[2:3], v[68:69], v[56:57]
	ds_read_b128 v[0:3], v59 offset:38912
	v_sub_f32_e32 v69, v75, v63
	v_sub_f32_e32 v68, v74, v62
	v_sub_f32_e32 v71, v73, v65
	v_sub_f32_e32 v70, v72, v64
	s_waitcnt lgkmcnt(0)
	v_pk_fma_f32 v[0:1], v[0:1], v[68:69], v[62:63]
	v_add_co_u32_e32 v62, vcc, s70, v66
	v_pk_fma_f32 v[2:3], v[2:3], v[70:71], v[64:65]
	s_nop 0
	v_addc_co_u32_e32 v63, vcc, 0, v67, vcc
	s_waitcnt vmcnt(15)
	v_mov_b32_e32 v62, v192
	v_mov_b32_e32 v63, v193
	v_lshl_add_u64 v[70:71], s[74:75], 0, v[22:23]
	v_lshl_add_u64 v[22:23], v[22:23], 0, s[46:47]
	v_lshlrev_b32_e32 v64, 16, v62
	v_and_b32_e32 v65, 0xffff0000, v62
	v_lshlrev_b32_e32 v62, 16, v63
	v_and_b32_e32 v63, 0xffff0000, v63
	v_pk_add_f32 v[62:63], v[62:63], -1.0 op_sel_hi:[1,0]
	v_pk_add_f32 v[64:65], v[64:65], -1.0 op_sel_hi:[1,0]
	v_pk_fma_f32 v[44:45], v[44:45], v[62:63], 1.0 op_sel_hi:[1,1,0]
	v_pk_fma_f32 v[42:43], v[42:43], v[64:65], 1.0 op_sel_hi:[1,1,0]
	v_pk_mul_f32 v[44:45], v[56:57], v[44:45]
	v_pk_mul_f32 v[42:43], v[54:55], v[42:43]
	v_pk_mul_f32 v[44:45], v[52:53], v[44:45]
	v_pk_mul_f32 v[42:43], v[50:51], v[42:43]
	v_pk_mul_f32 v[6:7], v[6:7], v[44:45]
	v_pk_mul_f32 v[4:5], v[4:5], v[42:43]
	v_lshl_add_u64 v[50:51], s[54:55], 0, v[28:29]
	v_pk_mov_b32 v[42:43], v[4:5], v[6:7] op_sel:[1,0]
	v_mov_b32_e32 v5, v7
	v_pk_add_f32 v[4:5], v[42:43], v[4:5]
	s_nop 0
	v_add_f32_e32 v4, v4, v5
	s_nop 1
	v_add_f32_dpp v4, v4, v4 quad_perm:[1,0,3,2] row_mask:0xf bank_mask:0xf bound_ctrl:1
	s_nop 1
	v_add_f32_dpp v4, v4, v4 quad_perm:[2,3,0,1] row_mask:0xf bank_mask:0xf bound_ctrl:1
	s_nop 1
	v_add_f32_dpp v4, v4, v4 row_half_mirror row_mask:0xf bank_mask:0xf bound_ctrl:1
	s_nop 1
	v_add_f32_dpp v4, v4, v4 row_mirror row_mask:0xf bank_mask:0xf bound_ctrl:1
	v_pk_fma_f32 v[0:1], v[0:1], v[4:5], v[46:47] op_sel_hi:[1,0,1]
	v_pk_fma_f32 v[2:3], v[2:3], v[4:5], v[48:49] op_sel_hi:[1,0,1]
	s_waitcnt vmcnt(14)
	v_mov_b32_e32 v4, v194
	v_mov_b32_e32 v5, v195
	v_lshlrev_b32_e32 v6, 16, v4
	v_and_b32_e32 v7, 0xffff0000, v4
	v_lshlrev_b32_e32 v4, 16, v5
	v_and_b32_e32 v5, 0xffff0000, v5
	v_pk_mul_f32 v[2:3], v[2:3], v[4:5]
	v_pk_mul_f32 v[0:1], v[0:1], v[6:7]
	ds_write_b128 v60, v[0:3] offset:2048
	v_pk_mul_f32 v[4:5], v[2:3], v[2:3]
	v_pk_mul_f32 v[6:7], v[0:1], v[0:1]
	v_add_f32_e32 v44, v4, v5
	v_add_f32_e32 v42, v6, v7
	s_waitcnt vmcnt(13)
	v_mov_b32_e32 v4, v196
	v_mov_b32_e32 v5, v197
	v_mov_b32_e32 v6, v198
	v_mov_b32_e32 v7, v199
	s_nop 0
	s_waitcnt vmcnt(12)
	v_mov_b32_e32 v36, v200
	v_mov_b32_e32 v37, v201
	v_mov_b32_e32 v38, v202
	v_mov_b32_e32 v39, v203
	v_pk_add_f32 v[6:7], v[6:7], v[38:39]
	v_pk_add_f32 v[4:5], v[4:5], v[36:37]
	v_mov_b32_e32 v39, v7
	v_pk_mov_b32 v[36:37], v[4:5], v[6:7] op_sel:[1,0]
	v_mov_b32_e32 v38, v4
	v_pk_add_f32 v[36:37], v[36:37], v[38:39]
	s_nop 0
	v_add_f32_e32 v11, v36, v37
	s_nop 1
	v_add_f32_dpp v11, v11, v11 quad_perm:[1,0,3,2] row_mask:0xf bank_mask:0xf bound_ctrl:1
	s_nop 1
	v_add_f32_dpp v11, v11, v11 quad_perm:[2,3,0,1] row_mask:0xf bank_mask:0xf bound_ctrl:1
	s_nop 1
	v_add_f32_dpp v11, v11, v11 row_half_mirror row_mask:0xf bank_mask:0xf bound_ctrl:1
	s_nop 1
	v_add_f32_dpp v11, v11, v11 row_mirror row_mask:0xf bank_mask:0xf bound_ctrl:1
	v_fmamk_f32 v5, v11, 0xbc800000, v5
	v_fmac_f32_e32 v4, 0xbc800000, v11
	v_fmamk_f32 v7, v11, 0xbc800000, v7
	v_fmac_f32_e32 v6, 0xbc800000, v11
	v_pk_mul_f32 v[36:37], v[6:7], v[6:7]
	v_pk_mul_f32 v[38:39], v[4:5], v[4:5]
	s_nop 0
	v_pk_mov_b32 v[46:47], v[38:39], v[36:37] op_sel:[1,0]
	v_mov_b32_e32 v39, v37
	v_pk_add_f32 v[36:37], v[46:47], v[38:39]
	s_nop 0
	v_add_f32_e32 v11, v36, v37
	s_nop 1
	v_add_f32_dpp v11, v11, v11 quad_perm:[1,0,3,2] row_mask:0xf bank_mask:0xf bound_ctrl:1
	s_nop 1
	v_add_f32_dpp v11, v11, v11 quad_perm:[2,3,0,1] row_mask:0xf bank_mask:0xf bound_ctrl:1
	s_nop 1
	v_add_f32_dpp v11, v11, v11 row_half_mirror row_mask:0xf bank_mask:0xf bound_ctrl:1
	s_nop 1
	v_add_f32_dpp v11, v11, v11 row_mirror row_mask:0xf bank_mask:0xf bound_ctrl:1
	v_fmamk_f32 v11, v11, 0x3c800000, v84
	v_rsq_f32_e32 v36, v11
	s_nop 0
	v_pk_mul_f32 v[46:47], v[6:7], v[36:37] op_sel_hi:[1,0]
	v_pk_mul_f32 v[48:49], v[4:5], v[36:37] op_sel_hi:[1,0]
	ds_read_b128 v[4:7], v59 offset:3072
	ds_read_b128 v[36:39], v59 offset:7168
	s_waitcnt lgkmcnt(0)
	v_pk_fma_f32 v[4:5], v[4:5], v[48:49], v[36:37]
	v_lshl_add_u64 v[36:37], s[74:75], 0, v[28:29]
	v_pk_fma_f32 v[6:7], v[6:7], v[46:47], v[38:39]
	v_add_co_u32_e32 v38, vcc, s11, v36
	s_nop 1
	v_addc_co_u32_e32 v39, vcc, 0, v37, vcc
	v_add_co_u32_e32 v36, vcc, s13, v36
	s_waitcnt vmcnt(11)
	v_mov_b32_e32 v46, v204
	v_mov_b32_e32 v47, v205
	s_nop 0
	v_addc_co_u32_e32 v37, vcc, 0, v37, vcc
	s_waitcnt vmcnt(10)
	v_mov_b32_e32 v36, v206
	v_mov_b32_e32 v37, v207
	v_add_co_u32_e32 v52, vcc, s11, v50
	s_waitcnt vmcnt(9)
	v_mov_b32_e32 v38, v210
	v_mov_b32_e32 v39, v211
	s_nop 0
	v_addc_co_u32_e32 v53, vcc, 0, v51, vcc
	v_add_co_u32_e32 v50, vcc, s13, v50
	v_lshlrev_b32_e32 v54, 16, v46
	v_addc_co_u32_e32 v51, vcc, 0, v51, vcc
	v_and_b32_e32 v55, 0xffff0000, v46
	v_lshlrev_b32_e32 v56, 16, v47
	v_and_b32_e32 v57, 0xffff0000, v47
	v_lshlrev_b32_e32 v62, 16, v38
	v_and_b32_e32 v63, 0xffff0000, v38
	v_lshlrev_b32_e32 v64, 16, v39
	v_and_b32_e32 v65, 0xffff0000, v39
	v_lshlrev_b32_e32 v66, 16, v36
	v_and_b32_e32 v67, 0xffff0000, v36
	v_lshlrev_b32_e32 v68, 16, v37
	v_and_b32_e32 v69, 0xffff0000, v37
	ds_read_b128 v[36:39], v59 offset:11264
	ds_read_b128 v[46:49], v59 offset:15360
	s_waitcnt vmcnt(8)
	v_mov_b32_e32 v72, v212
	v_mov_b32_e32 v73, v213
	s_nop 0
	s_waitcnt vmcnt(7)
	v_mov_b32_e32 v50, v214
	v_mov_b32_e32 v51, v215
	v_lshlrev_b32_e32 v11, 16, v72
	s_waitcnt vmcnt(6)
	v_mov_b32_e32 v52, v216
	v_mov_b32_e32 v53, v217
	v_and_b32_e32 v41, 0xffff0000, v72
	v_lshlrev_b32_e32 v43, 16, v73
	v_and_b32_e32 v45, 0xffff0000, v73
	v_lshlrev_b32_e32 v73, 16, v50
	v_and_b32_e32 v50, 0xffff0000, v50
	v_lshlrev_b32_e32 v74, 16, v51
	v_and_b32_e32 v51, 0xffff0000, v51
	v_cndmask_b32_e64 v83, v50, 0, s[52:53]
	v_cndmask_b32_e64 v81, v51, 0, s[52:53]
	v_cndmask_b32_e64 v43, v43, 0, s[52:53]
	v_cndmask_b32_e64 v45, v45, 0, s[52:53]
	v_cndmask_b32_e64 v11, v11, 0, s[52:53]
	v_cndmask_b32_e64 v41, v41, 0, s[52:53]
	v_cndmask_b32_e64 v82, v73, 0, s[52:53]
	v_cndmask_b32_e64 v80, v74, 0, s[52:53]
	v_sub_f32_e32 v73, v41, v55
	v_sub_f32_e32 v75, v45, v57
	v_sub_f32_e32 v74, v43, v56
	v_sub_f32_e32 v81, v81, v69
	v_sub_f32_e32 v80, v80, v68
	v_sub_f32_e32 v83, v83, v67
	v_sub_f32_e32 v82, v82, v66
	s_waitcnt vmcnt(5)
	v_mov_b32_e32 v8, v218
	v_mov_b32_e32 v9, v219
	v_lshlrev_b32_e32 v61, 16, v52
	v_and_b32_e32 v52, 0xffff0000, v52
	v_lshlrev_b32_e32 v72, 16, v53
	v_and_b32_e32 v53, 0xffff0000, v53
	v_cndmask_b32_e64 v78, v52, 0, s[52:53]
	v_cndmask_b32_e64 v77, v53, 0, s[52:53]
	ds_read_b128 v[50:53], v59 offset:19456
	v_cndmask_b32_e64 v76, v72, 0, s[52:53]
	v_sub_f32_e32 v72, v11, v54
	v_cndmask_b32_e64 v61, v61, 0, s[52:53]
	v_sub_f32_e32 v77, v77, v65
	s_waitcnt lgkmcnt(0)
	v_pk_fma_f32 v[74:75], v[52:53], v[74:75], v[56:57]
	v_pk_fma_f32 v[72:73], v[50:51], v[72:73], v[54:55]
	ds_read_b128 v[50:53], v59 offset:23552
	v_sub_f32_e32 v76, v76, v64
	v_sub_f32_e32 v79, v78, v63
	v_sub_f32_e32 v78, v61, v62
	s_waitcnt lgkmcnt(0)
	v_pk_fma_f32 v[78:79], v[50:51], v[78:79], v[62:63]
	v_pk_fma_f32 v[76:77], v[52:53], v[76:77], v[64:65]
	ds_read_b128 v[50:53], v59 offset:27648
	s_waitcnt lgkmcnt(0)
	v_pk_fma_f32 v[52:53], v[52:53], v[80:81], v[68:69]
	v_add_co_u32_e32 v80, vcc, s97, v70
	v_pk_fma_f32 v[50:51], v[50:51], v[82:83], v[66:67]
	s_nop 0
	v_addc_co_u32_e32 v81, vcc, 0, v71, vcc
	s_waitcnt vmcnt(4)
	v_mov_b32_e32 v80, v220
	v_mov_b32_e32 v81, v221
	v_lshlrev_b32_e32 v82, 16, v80
	v_and_b32_e32 v83, 0xffff0000, v80
	v_lshlrev_b32_e32 v80, 16, v81
	v_and_b32_e32 v81, 0xffff0000, v81
	v_pk_add_f32 v[80:81], v[80:81], -1.0 op_sel_hi:[1,0]
	v_pk_add_f32 v[82:83], v[82:83], -1.0 op_sel_hi:[1,0]
	v_pk_fma_f32 v[80:81], v[48:49], v[80:81], 1.0 op_sel_hi:[1,1,0]
	v_pk_fma_f32 v[82:83], v[46:47], v[82:83], 1.0 op_sel_hi:[1,1,0]
	v_pk_mul_f32 v[76:77], v[76:77], v[80:81]
	v_pk_mul_f32 v[78:79], v[78:79], v[82:83]
	v_pk_mul_f32 v[74:75], v[74:75], v[76:77]
	v_pk_mul_f32 v[72:73], v[72:73], v[78:79]
	v_pk_mul_f32 v[74:75], v[38:39], v[74:75]
	v_pk_mul_f32 v[72:73], v[36:37], v[72:73]
	s_nop 0
	v_pk_mov_b32 v[76:77], v[72:73], v[74:75] op_sel:[1,0]
	v_mov_b32_e32 v73, v75
	v_pk_add_f32 v[72:73], v[76:77], v[72:73]
	s_nop 0
	v_add_f32_e32 v11, v72, v73
	s_nop 1
	v_add_f32_dpp v11, v11, v11 quad_perm:[1,0,3,2] row_mask:0xf bank_mask:0xf bound_ctrl:1
	s_nop 1
	v_add_f32_dpp v11, v11, v11 quad_perm:[2,3,0,1] row_mask:0xf bank_mask:0xf bound_ctrl:1
	s_nop 1
	v_add_f32_dpp v11, v11, v11 row_half_mirror row_mask:0xf bank_mask:0xf bound_ctrl:1
	s_nop 1
	v_add_f32_dpp v72, v11, v11 row_mirror row_mask:0xf bank_mask:0xf bound_ctrl:1
	v_pk_fma_f32 v[50:51], v[50:51], v[72:73], v[4:5] op_sel_hi:[1,0,1]
	v_lshl_add_u64 v[4:5], s[56:57], 0, v[28:29]
	v_pk_fma_f32 v[52:53], v[52:53], v[72:73], v[6:7] op_sel_hi:[1,0,1]
	v_add_co_u32_e32 v6, vcc, s11, v4
	v_lshl_add_u64 v[28:29], v[28:29], 0, s[48:49]
	s_nop 0
	v_addc_co_u32_e32 v7, vcc, 0, v5, vcc
	v_add_co_u32_e32 v4, vcc, s13, v4
	s_waitcnt vmcnt(3)
	v_mov_b32_e32 v72, v222
	v_mov_b32_e32 v73, v223
	s_nop 0
	v_addc_co_u32_e32 v5, vcc, 0, v5, vcc
	s_waitcnt vmcnt(2)
	v_mov_b32_e32 v4, v224
	v_mov_b32_e32 v5, v225
	v_lshlrev_b32_e32 v11, 16, v72
	s_waitcnt vmcnt(1)
	v_mov_b32_e32 v6, v226
	v_mov_b32_e32 v7, v227
	v_and_b32_e32 v41, 0xffff0000, v72
	v_lshlrev_b32_e32 v43, 16, v73
	v_and_b32_e32 v45, 0xffff0000, v73
	v_lshlrev_b32_e32 v73, 16, v4
	v_and_b32_e32 v4, 0xffff0000, v4
	v_lshlrev_b32_e32 v74, 16, v5
	v_and_b32_e32 v5, 0xffff0000, v5
	v_cndmask_b32_e64 v77, v5, 0, s[50:51]
	v_cndmask_b32_e64 v79, v4, 0, s[50:51]
	v_cndmask_b32_e64 v43, v43, 0, s[50:51]
	v_cndmask_b32_e64 v45, v45, 0, s[50:51]
	v_cndmask_b32_e64 v11, v11, 0, s[50:51]
	v_cndmask_b32_e64 v41, v41, 0, s[50:51]
	v_cndmask_b32_e64 v76, v74, 0, s[50:51]
	v_cndmask_b32_e64 v78, v73, 0, s[50:51]
	v_sub_f32_e32 v73, v41, v55
	v_sub_f32_e32 v75, v45, v57
	v_sub_f32_e32 v74, v43, v56
	v_lshlrev_b32_e32 v61, 16, v6
	v_and_b32_e32 v6, 0xffff0000, v6
	v_lshlrev_b32_e32 v72, 16, v7
	v_and_b32_e32 v7, 0xffff0000, v7
	v_cndmask_b32_e64 v80, v6, 0, s[50:51]
	v_cndmask_b32_e64 v82, v7, 0, s[50:51]
	ds_read_b128 v[4:7], v59 offset:31744
	v_cndmask_b32_e64 v81, v72, 0, s[50:51]
	v_sub_f32_e32 v72, v11, v54
	v_cndmask_b32_e64 v61, v61, 0, s[50:51]
	s_waitcnt lgkmcnt(0)
	v_pk_fma_f32 v[56:57], v[6:7], v[74:75], v[56:57]
	v_pk_fma_f32 v[54:55], v[4:5], v[72:73], v[54:55]
	ds_read_b128 v[4:7], v59 offset:35840
	v_sub_f32_e32 v73, v82, v65
	v_sub_f32_e32 v72, v81, v64
	v_sub_f32_e32 v75, v80, v63
	v_sub_f32_e32 v74, v61, v62
	s_waitcnt lgkmcnt(0)
	v_pk_fma_f32 v[62:63], v[4:5], v[74:75], v[62:63]
	v_pk_fma_f32 v[64:65], v[6:7], v[72:73], v[64:65]
	ds_read_b128 v[4:7], v59 offset:39936
	v_sub_f32_e32 v73, v79, v67
	v_sub_f32_e32 v72, v78, v66
	v_sub_f32_e32 v75, v77, v69
	v_sub_f32_e32 v74, v76, v68
	s_waitcnt lgkmcnt(0)
	v_pk_fma_f32 v[4:5], v[4:5], v[72:73], v[66:67]
	v_add_co_u32_e32 v66, vcc, s70, v70
	v_pk_fma_f32 v[6:7], v[6:7], v[74:75], v[68:69]
	s_nop 0
	v_addc_co_u32_e32 v67, vcc, 0, v71, vcc
	s_waitcnt vmcnt(0)
	v_mov_b32_e32 v66, v228
	v_mov_b32_e32 v67, v229
	v_lshlrev_b32_e32 v68, 16, v66
	v_and_b32_e32 v69, 0xffff0000, v66
	v_lshlrev_b32_e32 v66, 16, v67
	v_and_b32_e32 v67, 0xffff0000, v67
	v_pk_add_f32 v[66:67], v[66:67], -1.0 op_sel_hi:[1,0]
	v_pk_add_f32 v[68:69], v[68:69], -1.0 op_sel_hi:[1,0]
	v_pk_fma_f32 v[48:49], v[48:49], v[66:67], 1.0 op_sel_hi:[1,1,0]
	v_pk_fma_f32 v[46:47], v[46:47], v[68:69], 1.0 op_sel_hi:[1,1,0]
	v_pk_mul_f32 v[48:49], v[64:65], v[48:49]
	v_pk_mul_f32 v[46:47], v[62:63], v[46:47]
	v_pk_mul_f32 v[48:49], v[56:57], v[48:49]
	v_pk_mul_f32 v[46:47], v[54:55], v[46:47]
	v_pk_mul_f32 v[38:39], v[38:39], v[48:49]
	v_pk_mul_f32 v[36:37], v[36:37], v[46:47]
	s_nop 0
	v_pk_mov_b32 v[46:47], v[36:37], v[38:39] op_sel:[1,0]
	v_mov_b32_e32 v37, v39
	v_pk_add_f32 v[36:37], v[46:47], v[36:37]
	v_lshl_add_u64 v[38:39], s[74:75], 0, v[16:17]
	v_add_f32_e32 v11, v36, v37
	v_lshl_add_u64 v[16:17], v[16:17], 0, s[44:45]
	s_nop 0
	v_add_f32_dpp v11, v11, v11 quad_perm:[1,0,3,2] row_mask:0xf bank_mask:0xf bound_ctrl:1
	s_nop 1
	v_add_f32_dpp v11, v11, v11 quad_perm:[2,3,0,1] row_mask:0xf bank_mask:0xf bound_ctrl:1
	s_nop 1
	v_add_f32_dpp v11, v11, v11 row_half_mirror row_mask:0xf bank_mask:0xf bound_ctrl:1
	s_nop 1
	v_add_f32_dpp v36, v11, v11 row_mirror row_mask:0xf bank_mask:0xf bound_ctrl:1
	v_pk_fma_f32 v[4:5], v[4:5], v[36:37], v[50:51] op_sel_hi:[1,0,1]
	v_pk_fma_f32 v[6:7], v[6:7], v[36:37], v[52:53] op_sel_hi:[1,0,1]
	v_lshlrev_b32_e32 v36, 16, v8
	v_and_b32_e32 v37, 0xffff0000, v8
	v_lshlrev_b32_e32 v8, 16, v9
	v_and_b32_e32 v9, 0xffff0000, v9
	v_pk_mul_f32 v[6:7], v[6:7], v[8:9]
	v_pk_mul_f32 v[4:5], v[4:5], v[36:37]
	v_pk_mul_f32 v[8:9], v[6:7], v[6:7]
	v_pk_mul_f32 v[36:37], v[4:5], v[4:5]
	v_mov_b32_e32 v43, v8
	v_mov_b32_e32 v11, v36
	v_mov_b32_e32 v41, v37
	v_mov_b32_e32 v45, v9
	v_pk_add_f32 v[10:11], v[10:11], v[40:41]
	v_pk_add_f32 v[8:9], v[42:43], v[44:45]
	ds_write_b128 v60, v[4:7] offset:3072
	v_pk_add_f32 v[8:9], v[10:11], v[8:9]
	s_nop 0
	v_add_f32_e32 v8, v8, v9
	s_nop 1
	v_add_f32_dpp v8, v8, v8 quad_perm:[1,0,3,2] row_mask:0xf bank_mask:0xf bound_ctrl:1
	s_nop 1
	v_add_f32_dpp v8, v8, v8 quad_perm:[2,3,0,1] row_mask:0xf bank_mask:0xf bound_ctrl:1
	s_nop 1
	v_add_f32_dpp v8, v8, v8 row_half_mirror row_mask:0xf bank_mask:0xf bound_ctrl:1
	s_nop 1
	v_add_f32_dpp v8, v8, v8 row_mirror row_mask:0xf bank_mask:0xf bound_ctrl:1
	s_nop 0
	v_readlane_b32 s2, v8, 16
	v_readlane_b32 s6, v8, 48
	v_readlane_b32 s4, v8, 0
	v_readlane_b32 s5, v8, 32
	v_mov_b32_e32 v8, s2
	v_mov_b32_e32 v9, s6
	v_pk_add_f32 v[8:9], s[4:5], v[8:9]
	s_mov_b32 s2, 0x2fe00000
	v_add_f32_e32 v8, v8, v9
	v_fmamk_f32 v8, v8, 0x3a800000, v252
	v_rsq_f32_e32 v36, v8
	v_add_co_u32_e32 v8, vcc, s12, v38
	s_nop 1
	v_addc_co_u32_e32 v9, vcc, 0, v39, vcc
	global_load_dwordx4 v[8:11], v[8:9], off
	v_add_co_u32_e32 v38, vcc, s2, v38
	s_nop 1
	v_addc_co_u32_e32 v39, vcc, 0, v39, vcc
	global_load_dwordx4 v[38:41], v[38:39], off
	s_waitcnt vmcnt(1)
	v_lshlrev_b32_e32 v48, 16, v8
	v_and_b32_e32 v49, 0xffff0000, v8
	v_lshlrev_b32_e32 v52, 16, v10
	v_and_b32_e32 v53, 0xffff0000, v10
	v_lshlrev_b32_e32 v8, 16, v9
	v_and_b32_e32 v9, 0xffff0000, v9
	v_lshlrev_b32_e32 v54, 16, v11
	v_and_b32_e32 v55, 0xffff0000, v11
	v_pk_mul_f32 v[46:47], v[48:49], v[48:49]
	v_pk_mul_f32 v[56:57], v[52:53], v[52:53]
	v_pk_mul_f32 v[10:11], v[8:9], v[8:9]
	v_pk_mul_f32 v[50:51], v[54:55], v[54:55]
	v_mov_b32_e32 v62, v46
	v_mov_b32_e32 v63, v56
	v_mov_b32_e32 v56, v47
	v_pk_add_f32 v[46:47], v[62:63], v[56:57]
	v_mov_b32_e32 v56, v10
	v_mov_b32_e32 v57, v50
	v_mov_b32_e32 v50, v11
	v_pk_add_f32 v[10:11], v[56:57], v[50:51]
	s_waitcnt vmcnt(0)
	v_lshlrev_b32_e32 v42, 16, v38
	v_pk_add_f32 v[10:11], v[46:47], v[10:11]
	v_and_b32_e32 v43, 0xffff0000, v38
	v_add_f32_e32 v10, v10, v11
	v_lshlrev_b32_e32 v44, 16, v39
	v_and_b32_e32 v45, 0xffff0000, v39
	v_add_f32_dpp v10, v10, v10 quad_perm:[1,0,3,2] row_mask:0xf bank_mask:0xf bound_ctrl:1
	v_lshlrev_b32_e32 v38, 16, v40
	v_and_b32_e32 v39, 0xffff0000, v40
	v_add_f32_dpp v10, v10, v10 quad_perm:[2,3,0,1] row_mask:0xf bank_mask:0xf bound_ctrl:1
	v_lshlrev_b32_e32 v40, 16, v41
	v_and_b32_e32 v41, 0xffff0000, v41
	v_add_f32_dpp v10, v10, v10 row_half_mirror row_mask:0xf bank_mask:0xf bound_ctrl:1
	v_pk_mul_f32 v[46:47], v[42:43], v[42:43]
	v_pk_mul_f32 v[62:63], v[38:39], v[38:39]
	v_add_f32_dpp v10, v10, v10 row_mirror row_mask:0xf bank_mask:0xf bound_ctrl:1
	v_pk_mul_f32 v[50:51], v[40:41], v[40:41]
	v_readlane_b32 s2, v10, 16
	v_readlane_b32 s6, v10, 48
	v_readlane_b32 s4, v10, 0
	v_readlane_b32 s5, v10, 32
	v_mov_b32_e32 v10, s2
	v_mov_b32_e32 v11, s6
	v_pk_add_f32 v[10:11], s[4:5], v[10:11]
	v_mov_b32_e32 v64, v46
	v_add_f32_e32 v10, v10, v11
	v_fmamk_f32 v10, v10, 0x3b000000, v252
	v_rsq_f32_e32 v56, v10
	v_pk_mul_f32 v[10:11], v[44:45], v[44:45]
	v_mov_b32_e32 v65, v62
	v_mov_b32_e32 v62, v47
	v_pk_add_f32 v[46:47], v[64:65], v[62:63]
	v_mov_b32_e32 v62, v10
	v_mov_b32_e32 v63, v50
	v_mov_b32_e32 v50, v11
	v_pk_add_f32 v[10:11], v[62:63], v[50:51]
	v_pk_mul_f32 v[62:63], v[56:57], v[48:49] op_sel_hi:[0,1]
	v_pk_add_f32 v[10:11], v[46:47], v[10:11]
	v_pk_mul_f32 v[64:65], v[56:57], v[8:9] op_sel_hi:[0,1]
	v_add_f32_e32 v10, v10, v11
	v_pk_mul_f32 v[52:53], v[56:57], v[52:53] op_sel_hi:[0,1]
	v_pk_mul_f32 v[54:55], v[56:57], v[54:55] op_sel_hi:[0,1]
	v_add_f32_dpp v10, v10, v10 quad_perm:[1,0,3,2] row_mask:0xf bank_mask:0xf bound_ctrl:1
	s_nop 1
	v_add_f32_dpp v10, v10, v10 quad_perm:[2,3,0,1] row_mask:0xf bank_mask:0xf bound_ctrl:1
	s_nop 1
	v_add_f32_dpp v10, v10, v10 row_half_mirror row_mask:0xf bank_mask:0xf bound_ctrl:1
	s_nop 1
	v_add_f32_dpp v10, v10, v10 row_mirror row_mask:0xf bank_mask:0xf bound_ctrl:1
	s_nop 0
	v_readlane_b32 s2, v10, 16
	v_readlane_b32 s6, v10, 48
	v_readlane_b32 s4, v10, 0
	v_readlane_b32 s5, v10, 32
	v_mov_b32_e32 v10, s2
	v_mov_b32_e32 v11, s6
	v_pk_add_f32 v[10:11], s[4:5], v[10:11]
	s_nop 0
	v_add_f32_e32 v10, v10, v11
	v_fmamk_f32 v10, v10, 0x3b000000, v252
	v_rsq_f32_e32 v46, v10
	ds_read_b128 v[8:11], v58 offset:40960
	ds_read_b128 v[48:51], v58 offset:40976
	v_pk_mul_f32 v[42:43], v[46:47], v[42:43] op_sel_hi:[0,1]
	s_waitcnt lgkmcnt(1)
	v_pk_mul_f32 v[8:9], v[62:63], v[8:9]
	v_pk_mul_f32 v[10:11], v[64:65], v[10:11]
	v_bfe_u32 v37, v8, 16, 1
	v_add3_u32 v8, v8, v37, s3
	v_bfe_u32 v37, v9, 16, 1
	v_lshrrev_b32_e32 v8, 16, v8
	v_add3_u32 v9, v9, v37, s3
	v_and_or_b32 v8, v9, s29, v8
	v_bfe_u32 v9, v10, 16, 1
	v_add3_u32 v9, v10, v9, s3
	v_bfe_u32 v10, v11, 16, 1
	s_waitcnt lgkmcnt(0)
	v_pk_mul_f32 v[48:49], v[52:53], v[48:49]
	v_lshrrev_b32_e32 v9, 16, v9
	v_add3_u32 v10, v11, v10, s3
	v_and_or_b32 v9, v10, s29, v9
	v_bfe_u32 v10, v48, 16, 1
	v_add3_u32 v10, v48, v10, s3
	v_bfe_u32 v11, v49, 16, 1
	v_pk_mul_f32 v[50:51], v[54:55], v[50:51]
	v_lshrrev_b32_e32 v10, 16, v10
	v_add3_u32 v11, v49, v11, s3
	v_and_or_b32 v10, v11, s29, v10
	v_bfe_u32 v11, v50, 16, 1
	v_add3_u32 v11, v50, v11, s3
	v_bfe_u32 v37, v51, 16, 1
	v_lshl_add_u64 v[48:49], s[74:75], 0, v[14:15]
	v_lshrrev_b32_e32 v11, 16, v11
	v_add3_u32 v37, v51, v37, s3
	v_add_co_u32_e32 v48, vcc, s24, v48
	v_and_or_b32 v11, v37, s29, v11
	s_nop 0
	v_addc_co_u32_e32 v49, vcc, 0, v49, vcc
	global_store_dwordx4 v[48:49], v[8:11], off
	ds_read_b128 v[8:11], v58 offset:43008
	v_pk_mul_f32 v[44:45], v[46:47], v[44:45] op_sel_hi:[0,1]
	v_pk_mul_f32 v[38:39], v[46:47], v[38:39] op_sel_hi:[0,1]
	v_pk_mul_f32 v[40:41], v[46:47], v[40:41] op_sel_hi:[0,1]
	v_lshl_add_u64 v[14:15], v[14:15], 0, s[42:43]
	s_waitcnt lgkmcnt(0)
	v_pk_mul_f32 v[44:45], v[10:11], v[44:45]
	v_pk_mul_f32 v[42:43], v[8:9], v[42:43]
	ds_read_b128 v[8:11], v58 offset:43024
	v_bfe_u32 v37, v45, 16, 1
	v_add3_u32 v37, v45, v37, s3
	s_waitcnt lgkmcnt(0)
	v_pk_mul_f32 v[40:41], v[10:11], v[40:41]
	v_pk_mul_f32 v[10:11], v[8:9], v[38:39]
	v_bfe_u32 v8, v42, 16, 1
	v_add3_u32 v8, v42, v8, s3
	v_bfe_u32 v9, v43, 16, 1
	v_lshrrev_b32_e32 v8, 16, v8
	v_add3_u32 v9, v43, v9, s3
	v_and_or_b32 v8, v9, s29, v8
	v_bfe_u32 v9, v44, 16, 1
	v_add3_u32 v9, v44, v9, s3
	v_lshrrev_b32_e32 v9, 16, v9
	v_and_or_b32 v9, v37, s29, v9
	v_bfe_u32 v37, v10, 16, 1
	v_add3_u32 v10, v10, v37, s3
	v_bfe_u32 v37, v11, 16, 1
	v_lshrrev_b32_e32 v10, 16, v10
	v_add3_u32 v11, v11, v37, s3
	v_and_or_b32 v10, v11, s29, v10
	v_bfe_u32 v11, v40, 16, 1
	v_add3_u32 v11, v40, v11, s3
	v_bfe_u32 v37, v41, 16, 1
	v_lshrrev_b32_e32 v11, 16, v11
	v_add3_u32 v37, v41, v37, s3
	v_and_or_b32 v11, v37, s29, v11
	global_store_dwordx4 v[48:49], v[8:11], off offset:1024
	ds_read_b128 v[8:11], v60
	s_waitcnt lgkmcnt(0)
	v_pk_mul_f32 v[38:39], v[36:37], v[8:9] op_sel_hi:[0,1]
	v_pk_mul_f32 v[40:41], v[36:37], v[10:11] op_sel_hi:[0,1]
	ds_read_b128 v[8:11], v59 offset:45056
	s_waitcnt lgkmcnt(0)
	v_pk_mul_f32 v[8:9], v[38:39], v[8:9]
	s_nop 0
	v_bfe_u32 v37, v8, 16, 1
	v_add3_u32 v8, v8, v37, s3
	v_bfe_u32 v37, v9, 16, 1
	v_pk_mul_f32 v[10:11], v[40:41], v[10:11]
	v_lshrrev_b32_e32 v8, 16, v8
	v_add3_u32 v9, v9, v37, s3
	v_and_or_b32 v8, v9, s29, v8
	v_bfe_u32 v9, v10, 16, 1
	v_add3_u32 v9, v10, v9, s3
	v_bfe_u32 v10, v11, 16, 1
	v_lshrrev_b32_e32 v9, 16, v9
	v_add3_u32 v10, v11, v10, s3
	v_and_or_b32 v9, v10, s29, v9
	v_lshl_add_u64 v[10:11], s[74:75], 0, v[12:13]
	v_add_co_u32_e32 v38, vcc, s24, v10
	v_lshl_add_u64 v[12:13], v[12:13], 0, s[42:43]
	s_nop 0
	v_addc_co_u32_e32 v39, vcc, 0, v11, vcc
	global_store_dwordx2 v[38:39], v[8:9], off offset:2048
	ds_read_b128 v[8:11], v60 offset:1024
	s_waitcnt lgkmcnt(0)
	v_pk_mul_f32 v[40:41], v[36:37], v[8:9] op_sel_hi:[0,1]
	v_pk_mul_f32 v[42:43], v[36:37], v[10:11] op_sel_hi:[0,1]
	ds_read_b128 v[8:11], v59 offset:46080
	s_waitcnt lgkmcnt(0)
	v_pk_mul_f32 v[8:9], v[40:41], v[8:9]
	s_nop 0
	v_bfe_u32 v37, v8, 16, 1
	v_add3_u32 v8, v8, v37, s3
	v_bfe_u32 v37, v9, 16, 1
	v_pk_mul_f32 v[10:11], v[42:43], v[10:11]
	v_lshrrev_b32_e32 v8, 16, v8
	v_add3_u32 v9, v9, v37, s3
	v_and_or_b32 v8, v9, s29, v8
	v_bfe_u32 v9, v10, 16, 1
	v_add3_u32 v9, v10, v9, s3
	v_bfe_u32 v10, v11, 16, 1
	v_lshrrev_b32_e32 v9, 16, v9
	v_add3_u32 v10, v11, v10, s3
	v_and_or_b32 v9, v10, s29, v9
	global_store_dwordx2 v[38:39], v[8:9], off offset:2560
	v_pk_mul_f32 v[8:9], v[0:1], v[36:37] op_sel_hi:[1,0]
	v_pk_mul_f32 v[10:11], v[2:3], v[36:37] op_sel_hi:[1,0]
	ds_read_b128 v[0:3], v59 offset:47104
	v_pk_mul_f32 v[4:5], v[36:37], v[4:5] op_sel_hi:[0,1]
	v_pk_mul_f32 v[6:7], v[36:37], v[6:7] op_sel_hi:[0,1]
	s_waitcnt lgkmcnt(0)
	v_pk_mul_f32 v[0:1], v[8:9], v[0:1]
	s_nop 0
	v_bfe_u32 v8, v0, 16, 1
	v_add3_u32 v0, v0, v8, s3
	v_bfe_u32 v8, v1, 16, 1
	v_pk_mul_f32 v[2:3], v[10:11], v[2:3]
	v_lshrrev_b32_e32 v0, 16, v0
	v_add3_u32 v1, v1, v8, s3
	v_and_or_b32 v0, v1, s29, v0
	v_bfe_u32 v1, v2, 16, 1
	v_add3_u32 v1, v2, v1, s3
	v_bfe_u32 v2, v3, 16, 1
	v_lshrrev_b32_e32 v1, 16, v1
	v_add3_u32 v2, v3, v2, s3
	v_and_or_b32 v1, v2, s29, v1
	global_store_dwordx2 v[38:39], v[0:1], off offset:3072
	ds_read_b128 v[0:3], v59 offset:48128
	s_waitcnt lgkmcnt(0)
	v_pk_mul_f32 v[0:1], v[4:5], v[0:1]
	s_nop 0
	v_bfe_u32 v4, v0, 16, 1
	v_add3_u32 v0, v0, v4, s3
	v_bfe_u32 v4, v1, 16, 1
	v_pk_mul_f32 v[2:3], v[6:7], v[2:3]
	v_lshrrev_b32_e32 v0, 16, v0
	v_add3_u32 v1, v1, v4, s3
	v_and_or_b32 v0, v1, s29, v0
	v_bfe_u32 v1, v2, 16, 1
	v_add3_u32 v1, v2, v1, s3
	v_bfe_u32 v2, v3, 16, 1
	v_lshrrev_b32_e32 v1, 16, v1
	v_add3_u32 v2, v3, v2, s3
	v_and_or_b32 v1, v2, s29, v1
	global_store_dwordx2 v[38:39], v[0:1], off offset:3584
	s_cbranch_scc1 .LBB0_1304
	v_mov_b32_e32 v252, 0x358637bd
